# GEMM up-proj epilogue: dropped per-block vmcnt(0) store-ack waits; M3 loads hoisted
# speedup vs baseline: 1.0306x; 1.0009x over previous
.LBB0_67:
	s_or_b64 exec, exec, s[14:15]
	ds_bpermute_b32 v191, v194, v189
	v_mul_f32_e32 v64, 0xbfb8aa3b, v193
	v_exp_f32_e32 v66, v64
	v_lshlrev_b32_e32 v112, 2, v186
	s_waitcnt vmcnt(3)
	v_and_b32_e32 v77, 0xffff0000, v185
	s_waitcnt lgkmcnt(0)
	v_pk_add_f32 v[64:65], v[188:189], v[190:191]
	s_nop 0
	v_fmac_f32_e32 v65, v182, v64
	v_max_f32_e64 v64, |v65|, v66
	v_div_scale_f32 v65, s[0:1], v64, v64, 1.0
	v_rcp_f32_e32 v66, v65
	v_div_scale_f32 v67, vcc, 1.0, v64, 1.0
	s_load_dwordx2 s[0:1], s[8:9], 0x70
	v_fma_f32 v68, -v65, v66, 1.0
	v_fmac_f32_e32 v66, v68, v66
	v_mul_f32_e32 v68, v67, v66
	v_fma_f32 v69, -v65, v68, v67
	v_fmac_f32_e32 v68, v69, v66
	v_fma_f32 v65, -v65, v68, v67
	v_div_fmas_f32 v65, v65, v66, v68
	v_div_fixup_f32 v70, v65, v64, 1.0
	v_pk_mul_f32 v[68:69], v[48:49], v[70:71] op_sel_hi:[1,0]
	v_pk_mul_f32 v[66:67], v[50:51], v[70:71] op_sel_hi:[1,0]
	v_mul_f32_e32 v76, v69, v69
	v_fmac_f32_e32 v76, v68, v68
	v_fmac_f32_e32 v76, v66, v66
	v_pk_mul_f32 v[64:65], v[52:53], v[70:71] op_sel_hi:[1,0]
	v_fmac_f32_e32 v76, v67, v67
	v_fmac_f32_e32 v76, v64, v64
	v_pk_mul_f32 v[54:55], v[54:55], v[70:71] op_sel_hi:[1,0]
	v_fmac_f32_e32 v76, v65, v65
	v_fmac_f32_e32 v76, v54, v54
	v_pk_mul_f32 v[56:57], v[56:57], v[70:71] op_sel_hi:[1,0]
	v_fmac_f32_e32 v76, v55, v55
	v_fmac_f32_e32 v76, v56, v56
	v_pk_mul_f32 v[58:59], v[58:59], v[70:71] op_sel_hi:[1,0]
	v_fmac_f32_e32 v76, v57, v57
	v_fmac_f32_e32 v76, v58, v58
	v_pk_mul_f32 v[60:61], v[60:61], v[70:71] op_sel_hi:[1,0]
	v_fmac_f32_e32 v76, v59, v59
	v_fmac_f32_e32 v76, v60, v60
	v_pk_mul_f32 v[62:63], v[62:63], v[70:71] op_sel_hi:[1,0]
	v_fmac_f32_e32 v76, v61, v61
	v_fmac_f32_e32 v76, v62, v62
	v_fmac_f32_e32 v76, v63, v63
	v_pk_mul_f32 v[52:53], v[32:33], v[70:71] op_sel_hi:[1,0]
	v_pk_mul_f32 v[50:51], v[34:35], v[70:71] op_sel_hi:[1,0]
	v_fmac_f32_e32 v76, v52, v52
	v_fmac_f32_e32 v76, v53, v53
	v_fmac_f32_e32 v76, v50, v50
	v_pk_mul_f32 v[48:49], v[36:37], v[70:71] op_sel_hi:[1,0]
	v_fmac_f32_e32 v76, v51, v51
	v_fmac_f32_e32 v76, v48, v48
	v_pk_mul_f32 v[38:39], v[38:39], v[70:71] op_sel_hi:[1,0]
	v_fmac_f32_e32 v76, v49, v49
	v_fmac_f32_e32 v76, v38, v38
	v_pk_mul_f32 v[40:41], v[40:41], v[70:71] op_sel_hi:[1,0]
	v_fmac_f32_e32 v76, v39, v39
	v_fmac_f32_e32 v76, v40, v40
	v_pk_mul_f32 v[42:43], v[42:43], v[70:71] op_sel_hi:[1,0]
	v_fmac_f32_e32 v76, v41, v41
	v_fmac_f32_e32 v76, v42, v42
	v_pk_mul_f32 v[44:45], v[44:45], v[70:71] op_sel_hi:[1,0]
	v_fmac_f32_e32 v76, v43, v43
	v_fmac_f32_e32 v76, v44, v44
	s_waitcnt lgkmcnt(0)
	s_add_u32 s0, s0, s18
	v_pk_mul_f32 v[46:47], v[46:47], v[70:71] op_sel_hi:[1,0]
	v_fmac_f32_e32 v76, v45, v45
	s_addc_u32 s1, s1, 0
	v_fmac_f32_e32 v76, v46, v46
	v_pk_mul_f32 v[32:33], v[20:21], v[70:71] op_sel_hi:[1,0]
	v_pk_mul_f32 v[20:21], v[0:1], v[70:71] op_sel_hi:[1,0]
	v_lshl_add_u64 v[0:1], v[162:163], 2, s[0:1]
	v_fmac_f32_e32 v76, v47, v47
	v_pk_mul_f32 v[36:37], v[16:17], v[70:71] op_sel_hi:[1,0]
	v_pk_mul_f32 v[16:17], v[10:11], v[70:71] op_sel_hi:[1,0]
	v_pk_mul_f32 v[10:11], v[12:13], v[70:71] op_sel_hi:[1,0]
	v_pk_mul_f32 v[12:13], v[14:15], v[70:71] op_sel_hi:[1,0]
	v_pk_mul_f32 v[14:15], v[2:3], v[70:71] op_sel_hi:[1,0]
	v_lshl_add_u64 v[2:3], v[0:1], 0, v[112:113]
	v_pk_mul_f32 v[30:31], v[30:31], v[70:71] op_sel_hi:[1,0]
	v_pk_mul_f32 v[28:29], v[28:29], v[70:71] op_sel_hi:[1,0]
	v_pk_mul_f32 v[26:27], v[26:27], v[70:71] op_sel_hi:[1,0]
	v_pk_mul_f32 v[24:25], v[24:25], v[70:71] op_sel_hi:[1,0]
	v_pk_mul_f32 v[22:23], v[22:23], v[70:71] op_sel_hi:[1,0]
	v_pk_mul_f32 v[34:35], v[18:19], v[70:71] op_sel_hi:[1,0]
	v_fmac_f32_e32 v76, v36, v36
	v_pk_mul_f32 v[8:9], v[8:9], v[70:71] op_sel_hi:[1,0]
	v_pk_mul_f32 v[6:7], v[6:7], v[70:71] op_sel_hi:[1,0]
	v_pk_mul_f32 v[4:5], v[4:5], v[70:71] op_sel_hi:[1,0]
	global_load_dwordx4 v[96:99], v[2:3], off
	global_load_dwordx4 v[100:103], v[2:3], off offset:32
	global_load_dwordx4 v[104:107], v[2:3], off offset:64
	global_load_dwordx4 v[108:111], v[2:3], off offset:96
	global_load_dwordx4 v[114:117], v[2:3], off offset:128
	global_load_dwordx4 v[118:121], v[2:3], off offset:160
	global_load_dwordx4 v[122:125], v[2:3], off offset:192
	global_load_dwordx4 v[126:129], v[2:3], off offset:224
	global_load_dwordx4 v[130:133], v[2:3], off offset:256
	global_load_dwordx4 v[134:137], v[2:3], off offset:288
	global_load_dwordx4 v[138:141], v[2:3], off offset:320
	global_load_dwordx4 v[142:145], v[2:3], off offset:352
	global_load_dwordx4 v[146:149], v[2:3], off offset:384
	global_load_dwordx4 v[150:153], v[2:3], off offset:416
	global_load_dwordx4 v[154:157], v[2:3], off offset:448
	global_load_dwordx4 v[158:161], v[2:3], off offset:480
	v_fmac_f32_e32 v76, v37, v37
	v_fmac_f32_e32 v76, v34, v34
	v_fmac_f32_e32 v76, v35, v35
	v_fmac_f32_e32 v76, v32, v32
	v_fmac_f32_e32 v76, v33, v33
	v_fmac_f32_e32 v76, v22, v22
	v_fmac_f32_e32 v76, v23, v23
	v_fmac_f32_e32 v76, v24, v24
	v_fmac_f32_e32 v76, v25, v25
	v_fmac_f32_e32 v76, v26, v26
	v_fmac_f32_e32 v76, v27, v27
	v_fmac_f32_e32 v76, v28, v28
	v_fmac_f32_e32 v76, v29, v29
	v_fmac_f32_e32 v76, v30, v30
	v_fmac_f32_e32 v76, v31, v31
	v_fmac_f32_e32 v76, v20, v20
	v_fmac_f32_e32 v76, v21, v21
	v_fmac_f32_e32 v76, v14, v14
	v_fmac_f32_e32 v76, v15, v15
	v_fmac_f32_e32 v76, v4, v4
	v_fmac_f32_e32 v76, v5, v5
	v_fmac_f32_e32 v76, v6, v6
	v_fmac_f32_e32 v76, v7, v7
	v_fmac_f32_e32 v76, v8, v8
	v_fmac_f32_e32 v76, v9, v9
	v_pk_mul_f32 v[74:75], v[16:17], v[16:17]
	v_pk_mul_f32 v[18:19], v[10:11], v[10:11]
	v_add_f32_e32 v74, v74, v76
	v_add_f32_e32 v74, v75, v74
	v_add_f32_e32 v18, v18, v74
	v_pk_mul_f32 v[0:1], v[12:13], v[12:13]
	v_add_f32_e32 v18, v19, v18
	v_add_f32_e32 v0, v0, v18
	v_add_f32_e32 v0, v1, v0
	ds_bpermute_b32 v1, v194, v0
	s_mov_b32 s0, 0xf800000
	v_lshlrev_b32_e32 v76, 16, v185
	v_lshlrev_b32_e32 v112, 1, v186
	s_add_i32 s5, s5, s4
	s_waitcnt lgkmcnt(0)
	v_add_f32_e32 v0, v0, v1
	v_fmamk_f32 v0, v0, 0x3c000000, v225
	v_mul_f32_e32 v1, 0x4f800000, v0
	v_cmp_gt_f32_e32 vcc, s0, v0
	s_add_i32 s19, s19, s4
	s_cmpk_gt_i32 s5, 0xff
	v_cndmask_b32_e32 v0, v0, v1, vcc
	v_sqrt_f32_e32 v1, v0
	s_nop 0
	v_add_u32_e32 v18, -1, v1
	v_fma_f32 v19, -v18, v1, v0
	v_cmp_ge_f32_e64 s[38:39], 0, v19
	v_add_u32_e32 v19, 1, v1
	s_nop 0
	v_cndmask_b32_e64 v18, v1, v18, s[38:39]
	v_fma_f32 v1, -v19, v1, v0
	v_cmp_lt_f32_e64 s[38:39], 0, v1
	s_nop 1
	v_cndmask_b32_e64 v1, v18, v19, s[38:39]
	v_mul_f32_e32 v18, 0x37800000, v1
	v_cndmask_b32_e32 v1, v1, v18, vcc
	v_cmp_class_f32_e32 vcc, v0, v226
	s_nop 1
	v_cndmask_b32_e32 v0, v1, v0, vcc
	v_div_scale_f32 v1, s[0:1], v0, v0, 1.0
	v_rcp_f32_e32 v18, v1
	s_mov_b32 s0, 0x1e00000
	v_fma_f32 v19, -v1, v18, 1.0
	v_fmac_f32_e32 v18, v19, v18
	v_div_scale_f32 v19, vcc, 1.0, v0, 1.0
	v_mul_f32_e32 v74, v19, v18
	v_fma_f32 v75, -v1, v74, v19
	v_fmac_f32_e32 v74, v75, v18
	v_fma_f32 v1, -v1, v74, v19
	v_div_fmas_f32 v1, v1, v18, v74
	v_div_fixup_f32 v0, v1, v0, 1.0
	v_lshlrev_b32_e32 v1, 16, v184
	v_and_b32_e32 v74, 0xffff0000, v184
	v_mul_f32_e32 v1, 0xbfb8aa3b, v1
	v_exp_f32_e32 v1, v1
	v_mul_f32_e32 v74, 0xbfb8aa3b, v74
	v_exp_f32_e32 v75, v74
	v_lshlrev_b64 v[18:19], 11, v[164:165]
	v_add_f32_e32 v1, 1.0, v1
	v_rcp_f32_e32 v74, v1
	v_add_f32_e32 v1, 1.0, v75
	v_rcp_f32_e32 v75, v1
	v_pk_mul_f32 v[68:69], v[68:69], v[0:1] op_sel_hi:[1, 0]
	v_mul_f32_e32 v1, 0xbfb8aa3b, v76
	v_exp_f32_e32 v1, v1
	v_mul_f32_e32 v76, 0xbfb8aa3b, v77
	v_exp_f32_e32 v76, v76
	s_waitcnt vmcnt(15)
	v_pk_mul_f32 v[68:69], v[96:97], v[68:69]
	v_add_f32_e32 v1, 1.0, v1
	v_rcp_f32_e32 v70, v1
	v_add_f32_e32 v1, 1.0, v76
	v_rcp_f32_e32 v71, v1
	v_lshl_add_u64 v[18:19], s[2:3], 0, v[18:19]
	v_pk_mul_f32 v[66:67], v[66:67], v[0:1] op_sel_hi:[1, 0]
	v_lshl_add_u64 v[18:19], v[162:163], 1, v[18:19]
	v_pk_mul_f32 v[66:67], v[98:99], v[66:67]
	v_pk_mul_f32 v[68:69], v[74:75], v[68:69]
	v_pk_mul_f32 v[66:67], v[70:71], v[66:67]
	v_lshl_add_u64 v[18:19], v[18:19], 0, v[112:113]
	v_cvt_pk_bf16_f32 v68, v68, v69
	v_cvt_pk_bf16_f32 v69, v66, v67
	v_add_co_u32_e32 v66, vcc, s0, v18
	v_lshlrev_b32_e32 v1, 16, v180
	s_nop 0
	v_addc_co_u32_e32 v67, vcc, 0, v19, vcc
	global_store_dwordx2 v[66:67], v[68:69], off offset:1024
	v_and_b32_e32 v70, 0xffff0000, v180
	v_mul_f32_e32 v1, 0xbfb8aa3b, v1
	v_exp_f32_e32 v1, v1
	v_mul_f32_e32 v70, 0xbfb8aa3b, v70
	v_exp_f32_e32 v71, v70
	v_lshlrev_b32_e32 v72, 16, v181
	v_add_f32_e32 v1, 1.0, v1
	v_rcp_f32_e32 v70, v1
	v_add_f32_e32 v1, 1.0, v71
	v_and_b32_e32 v73, 0xffff0000, v181
	v_rcp_f32_e32 v71, v1
	v_pk_mul_f32 v[64:65], v[64:65], v[0:1] op_sel_hi:[1, 0]
	v_mul_f32_e32 v1, 0xbfb8aa3b, v72
	v_exp_f32_e32 v1, v1
	v_mul_f32_e32 v72, 0xbfb8aa3b, v73
	v_exp_f32_e32 v72, v72
	s_mov_b64 s[0:1], 0x1e00400
	v_add_f32_e32 v1, 1.0, v1
	v_lshl_add_u64 v[18:19], v[18:19], 0, s[0:1]
	s_waitcnt vmcnt(15)
	v_pk_mul_f32 v[64:65], v[100:101], v[64:65]
	v_rcp_f32_e32 v66, v1
	v_add_f32_e32 v1, 1.0, v72
	v_rcp_f32_e32 v67, v1
	v_pk_mul_f32 v[54:55], v[54:55], v[0:1] op_sel_hi:[1, 0]
	v_pk_mul_f32 v[64:65], v[70:71], v[64:65]
	v_pk_mul_f32 v[54:55], v[102:103], v[54:55]
	v_cvt_pk_bf16_f32 v64, v64, v65
	v_pk_mul_f32 v[54:55], v[66:67], v[54:55]
	v_lshlrev_b32_e32 v1, 16, v176
	v_cvt_pk_bf16_f32 v65, v54, v55
	global_store_dwordx2 v[18:19], v[64:65], off offset:16
	v_and_b32_e32 v54, 0xffff0000, v176
	v_lshlrev_b32_e32 v55, 16, v177
	v_and_b32_e32 v68, 0xffff0000, v177
	v_mul_f32_e32 v1, 0xbfb8aa3b, v1
	v_mul_f32_e32 v54, 0xbfb8aa3b, v54
	v_mul_f32_e32 v55, 0xbfb8aa3b, v55
	v_mul_f32_e32 v68, 0xbfb8aa3b, v68
	v_exp_f32_e32 v1, v1
	v_exp_f32_e32 v54, v54
	v_exp_f32_e32 v55, v55
	v_exp_f32_e32 v68, v68
	v_add_f32_e32 v1, 1.0, v1
	v_add_f32_e32 v69, 1.0, v54
	v_add_f32_e32 v70, 1.0, v55
	v_add_f32_e32 v71, 1.0, v68
	v_rcp_f32_e32 v54, v1
	v_rcp_f32_e32 v55, v69
	v_rcp_f32_e32 v68, v70
	v_rcp_f32_e32 v69, v71
	v_pk_mul_f32 v[56:57], v[56:57], v[0:1] op_sel_hi:[1, 0]
	v_pk_mul_f32 v[58:59], v[58:59], v[0:1] op_sel_hi:[1, 0]
	v_lshlrev_b32_e32 v1, 16, v174
	v_mul_f32_e32 v1, 0xbfb8aa3b, v1
	v_exp_f32_e32 v1, v1
	s_waitcnt vmcnt(15)
	v_pk_mul_f32 v[56:57], v[104:105], v[56:57]
	v_pk_mul_f32 v[58:59], v[106:107], v[58:59]
	v_pk_mul_f32 v[54:55], v[54:55], v[56:57]
	v_pk_mul_f32 v[56:57], v[68:69], v[58:59]
	v_cvt_pk_bf16_f32 v54, v54, v55
	v_cvt_pk_bf16_f32 v55, v56, v57
	global_store_dwordx2 v[18:19], v[54:55], off offset:32
	v_and_b32_e32 v58, 0xffff0000, v174
	v_lshlrev_b32_e32 v59, 16, v175
	v_and_b32_e32 v64, 0xffff0000, v175
	v_mul_f32_e32 v58, 0xbfb8aa3b, v58
	v_mul_f32_e32 v59, 0xbfb8aa3b, v59
	v_mul_f32_e32 v64, 0xbfb8aa3b, v64
	v_exp_f32_e32 v58, v58
	v_exp_f32_e32 v59, v59
	v_exp_f32_e32 v64, v64
	v_add_f32_e32 v1, 1.0, v1
	v_add_f32_e32 v65, 1.0, v58
	v_add_f32_e32 v66, 1.0, v59
	v_add_f32_e32 v67, 1.0, v64
	v_rcp_f32_e32 v58, v1
	v_rcp_f32_e32 v59, v65
	v_rcp_f32_e32 v64, v66
	v_rcp_f32_e32 v65, v67
	v_pk_mul_f32 v[60:61], v[60:61], v[0:1] op_sel_hi:[1, 0]
	v_pk_mul_f32 v[62:63], v[62:63], v[0:1] op_sel_hi:[1, 0]
	v_lshlrev_b32_e32 v1, 16, v172
	v_mul_f32_e32 v1, 0xbfb8aa3b, v1
	v_exp_f32_e32 v1, v1
	s_waitcnt vmcnt(15)
	v_pk_mul_f32 v[54:55], v[108:109], v[60:61]
	v_pk_mul_f32 v[56:57], v[110:111], v[62:63]
	v_pk_mul_f32 v[54:55], v[58:59], v[54:55]
	v_pk_mul_f32 v[56:57], v[64:65], v[56:57]
	v_cvt_pk_bf16_f32 v54, v54, v55
	v_cvt_pk_bf16_f32 v55, v56, v57
	global_store_dwordx2 v[18:19], v[54:55], off offset:48
	v_and_b32_e32 v58, 0xffff0000, v172
	v_lshlrev_b32_e32 v59, 16, v173
	v_and_b32_e32 v60, 0xffff0000, v173
	v_mul_f32_e32 v58, 0xbfb8aa3b, v58
	v_mul_f32_e32 v59, 0xbfb8aa3b, v59
	v_mul_f32_e32 v60, 0xbfb8aa3b, v60
	v_exp_f32_e32 v58, v58
	v_exp_f32_e32 v59, v59
	v_exp_f32_e32 v60, v60
	v_add_f32_e32 v1, 1.0, v1
	v_add_f32_e32 v61, 1.0, v58
	v_add_f32_e32 v62, 1.0, v59
	v_add_f32_e32 v63, 1.0, v60
	v_rcp_f32_e32 v58, v1
	v_rcp_f32_e32 v59, v61
	v_rcp_f32_e32 v60, v62
	v_rcp_f32_e32 v61, v63
	v_pk_mul_f32 v[52:53], v[52:53], v[0:1] op_sel_hi:[1, 0]
	v_pk_mul_f32 v[50:51], v[50:51], v[0:1] op_sel_hi:[1, 0]
	v_lshlrev_b32_e32 v1, 16, v170
	v_mul_f32_e32 v1, 0xbfb8aa3b, v1
	v_exp_f32_e32 v1, v1
	s_waitcnt vmcnt(15)
	v_pk_mul_f32 v[52:53], v[114:115], v[52:53]
	v_pk_mul_f32 v[50:51], v[116:117], v[50:51]
	v_pk_mul_f32 v[52:53], v[58:59], v[52:53]
	v_pk_mul_f32 v[50:51], v[60:61], v[50:51]
	v_cvt_pk_bf16_f32 v52, v52, v53
	v_cvt_pk_bf16_f32 v53, v50, v51
	global_store_dwordx2 v[18:19], v[52:53], off offset:64
	v_and_b32_e32 v54, 0xffff0000, v170
	v_lshlrev_b32_e32 v55, 16, v171
	v_and_b32_e32 v56, 0xffff0000, v171
	v_mul_f32_e32 v54, 0xbfb8aa3b, v54
	v_mul_f32_e32 v55, 0xbfb8aa3b, v55
	v_mul_f32_e32 v56, 0xbfb8aa3b, v56
	v_exp_f32_e32 v54, v54
	v_exp_f32_e32 v55, v55
	v_exp_f32_e32 v56, v56
	v_add_f32_e32 v1, 1.0, v1
	v_add_f32_e32 v57, 1.0, v54
	v_add_f32_e32 v58, 1.0, v55
	v_add_f32_e32 v59, 1.0, v56
	v_rcp_f32_e32 v54, v1
	v_rcp_f32_e32 v55, v57
	v_rcp_f32_e32 v56, v58
	v_rcp_f32_e32 v57, v59
	v_pk_mul_f32 v[48:49], v[48:49], v[0:1] op_sel_hi:[1, 0]
	v_pk_mul_f32 v[38:39], v[38:39], v[0:1] op_sel_hi:[1, 0]
	v_lshlrev_b32_e32 v1, 16, v168
	v_mul_f32_e32 v1, 0xbfb8aa3b, v1
	v_exp_f32_e32 v1, v1
	s_waitcnt vmcnt(15)
	v_pk_mul_f32 v[48:49], v[118:119], v[48:49]
	v_pk_mul_f32 v[38:39], v[120:121], v[38:39]
	v_pk_mul_f32 v[48:49], v[54:55], v[48:49]
	v_pk_mul_f32 v[38:39], v[56:57], v[38:39]
	v_cvt_pk_bf16_f32 v48, v48, v49
	v_cvt_pk_bf16_f32 v49, v38, v39
	global_store_dwordx2 v[18:19], v[48:49], off offset:80
	v_and_b32_e32 v38, 0xffff0000, v168
	v_lshlrev_b32_e32 v39, 16, v169
	v_and_b32_e32 v52, 0xffff0000, v169
	v_mul_f32_e32 v38, 0xbfb8aa3b, v38
	v_mul_f32_e32 v39, 0xbfb8aa3b, v39
	v_mul_f32_e32 v52, 0xbfb8aa3b, v52
	v_exp_f32_e32 v38, v38
	v_exp_f32_e32 v39, v39
	v_exp_f32_e32 v52, v52
	v_add_f32_e32 v1, 1.0, v1
	v_add_f32_e32 v53, 1.0, v38
	v_add_f32_e32 v54, 1.0, v39
	v_add_f32_e32 v55, 1.0, v52
	v_rcp_f32_e32 v38, v1
	v_rcp_f32_e32 v39, v53
	v_rcp_f32_e32 v52, v54
	v_rcp_f32_e32 v53, v55
	v_pk_mul_f32 v[40:41], v[40:41], v[0:1] op_sel_hi:[1, 0]
	v_pk_mul_f32 v[42:43], v[42:43], v[0:1] op_sel_hi:[1, 0]
	v_lshlrev_b32_e32 v1, 16, v166
	v_mul_f32_e32 v1, 0xbfb8aa3b, v1
	v_exp_f32_e32 v1, v1
	s_waitcnt vmcnt(15)
	v_pk_mul_f32 v[40:41], v[122:123], v[40:41]
	v_pk_mul_f32 v[42:43], v[124:125], v[42:43]
	v_pk_mul_f32 v[38:39], v[38:39], v[40:41]
	v_pk_mul_f32 v[40:41], v[52:53], v[42:43]
	v_cvt_pk_bf16_f32 v38, v38, v39
	v_cvt_pk_bf16_f32 v39, v40, v41
	global_store_dwordx2 v[18:19], v[38:39], off offset:96
	v_and_b32_e32 v42, 0xffff0000, v166
	v_lshlrev_b32_e32 v43, 16, v167
	v_and_b32_e32 v48, 0xffff0000, v167
	v_mul_f32_e32 v42, 0xbfb8aa3b, v42
	v_mul_f32_e32 v43, 0xbfb8aa3b, v43
	v_mul_f32_e32 v48, 0xbfb8aa3b, v48
	v_exp_f32_e32 v42, v42
	v_exp_f32_e32 v43, v43
	v_exp_f32_e32 v48, v48
	v_add_f32_e32 v1, 1.0, v1
	v_add_f32_e32 v49, 1.0, v42
	v_add_f32_e32 v50, 1.0, v43
	v_add_f32_e32 v51, 1.0, v48
	v_rcp_f32_e32 v42, v1
	v_rcp_f32_e32 v43, v49
	v_rcp_f32_e32 v48, v50
	v_rcp_f32_e32 v49, v51
	v_pk_mul_f32 v[44:45], v[44:45], v[0:1] op_sel_hi:[1, 0]
	v_pk_mul_f32 v[46:47], v[46:47], v[0:1] op_sel_hi:[1, 0]
	v_lshlrev_b32_e32 v1, 16, v94
	v_mul_f32_e32 v1, 0xbfb8aa3b, v1
	v_exp_f32_e32 v1, v1
	s_waitcnt vmcnt(15)
	v_pk_mul_f32 v[38:39], v[126:127], v[44:45]
	v_pk_mul_f32 v[40:41], v[128:129], v[46:47]
	v_pk_mul_f32 v[38:39], v[42:43], v[38:39]
	v_pk_mul_f32 v[40:41], v[48:49], v[40:41]
	v_cvt_pk_bf16_f32 v38, v38, v39
	v_cvt_pk_bf16_f32 v39, v40, v41
	global_store_dwordx2 v[18:19], v[38:39], off offset:112
	v_and_b32_e32 v42, 0xffff0000, v94
	v_lshlrev_b32_e32 v43, 16, v95
	v_and_b32_e32 v44, 0xffff0000, v95
	v_mul_f32_e32 v42, 0xbfb8aa3b, v42
	v_mul_f32_e32 v43, 0xbfb8aa3b, v43
	v_mul_f32_e32 v44, 0xbfb8aa3b, v44
	v_exp_f32_e32 v42, v42
	v_exp_f32_e32 v43, v43
	v_exp_f32_e32 v44, v44
	v_add_f32_e32 v1, 1.0, v1
	v_add_f32_e32 v45, 1.0, v42
	v_add_f32_e32 v46, 1.0, v43
	v_add_f32_e32 v47, 1.0, v44
	v_rcp_f32_e32 v42, v1
	v_rcp_f32_e32 v43, v45
	v_rcp_f32_e32 v44, v46
	v_rcp_f32_e32 v45, v47
	v_pk_mul_f32 v[36:37], v[36:37], v[0:1] op_sel_hi:[1, 0]
	v_pk_mul_f32 v[34:35], v[34:35], v[0:1] op_sel_hi:[1, 0]
	v_lshlrev_b32_e32 v1, 16, v92
	v_mul_f32_e32 v1, 0xbfb8aa3b, v1
	v_exp_f32_e32 v1, v1
	s_waitcnt vmcnt(15)
	v_pk_mul_f32 v[36:37], v[130:131], v[36:37]
	v_pk_mul_f32 v[34:35], v[132:133], v[34:35]
	v_pk_mul_f32 v[36:37], v[42:43], v[36:37]
	v_pk_mul_f32 v[34:35], v[44:45], v[34:35]
	v_cvt_pk_bf16_f32 v36, v36, v37
	v_cvt_pk_bf16_f32 v37, v34, v35
	global_store_dwordx2 v[18:19], v[36:37], off offset:128
	v_and_b32_e32 v38, 0xffff0000, v92
	v_lshlrev_b32_e32 v39, 16, v93
	v_and_b32_e32 v40, 0xffff0000, v93
	v_mul_f32_e32 v38, 0xbfb8aa3b, v38
	v_mul_f32_e32 v39, 0xbfb8aa3b, v39
	v_mul_f32_e32 v40, 0xbfb8aa3b, v40
	v_exp_f32_e32 v38, v38
	v_exp_f32_e32 v39, v39
	v_exp_f32_e32 v40, v40
	v_add_f32_e32 v1, 1.0, v1
	v_add_f32_e32 v41, 1.0, v38
	v_add_f32_e32 v42, 1.0, v39
	v_add_f32_e32 v43, 1.0, v40
	v_rcp_f32_e32 v38, v1
	v_rcp_f32_e32 v39, v41
	v_rcp_f32_e32 v40, v42
	v_rcp_f32_e32 v41, v43
	v_pk_mul_f32 v[32:33], v[32:33], v[0:1] op_sel_hi:[1, 0]
	v_pk_mul_f32 v[22:23], v[22:23], v[0:1] op_sel_hi:[1, 0]
	v_lshlrev_b32_e32 v1, 16, v90
	v_mul_f32_e32 v1, 0xbfb8aa3b, v1
	v_exp_f32_e32 v1, v1
	s_waitcnt vmcnt(15)
	v_pk_mul_f32 v[32:33], v[134:135], v[32:33]
	v_pk_mul_f32 v[22:23], v[136:137], v[22:23]
	v_pk_mul_f32 v[32:33], v[38:39], v[32:33]
	v_pk_mul_f32 v[22:23], v[40:41], v[22:23]
	v_cvt_pk_bf16_f32 v32, v32, v33
	v_cvt_pk_bf16_f32 v33, v22, v23
	global_store_dwordx2 v[18:19], v[32:33], off offset:144
	v_and_b32_e32 v22, 0xffff0000, v90
	v_lshlrev_b32_e32 v23, 16, v91
	v_and_b32_e32 v36, 0xffff0000, v91
	v_mul_f32_e32 v22, 0xbfb8aa3b, v22
	v_mul_f32_e32 v23, 0xbfb8aa3b, v23
	v_mul_f32_e32 v36, 0xbfb8aa3b, v36
	v_exp_f32_e32 v22, v22
	v_exp_f32_e32 v23, v23
	v_exp_f32_e32 v36, v36
	v_add_f32_e32 v1, 1.0, v1
	v_add_f32_e32 v37, 1.0, v22
	v_add_f32_e32 v38, 1.0, v23
	v_add_f32_e32 v39, 1.0, v36
	v_rcp_f32_e32 v22, v1
	v_rcp_f32_e32 v23, v37
	v_rcp_f32_e32 v36, v38
	v_rcp_f32_e32 v37, v39
	v_pk_mul_f32 v[24:25], v[24:25], v[0:1] op_sel_hi:[1, 0]
	v_pk_mul_f32 v[26:27], v[26:27], v[0:1] op_sel_hi:[1, 0]
	v_lshlrev_b32_e32 v1, 16, v88
	v_mul_f32_e32 v1, 0xbfb8aa3b, v1
	v_exp_f32_e32 v1, v1
	s_waitcnt vmcnt(15)
	v_pk_mul_f32 v[24:25], v[138:139], v[24:25]
	v_pk_mul_f32 v[26:27], v[140:141], v[26:27]
	v_pk_mul_f32 v[22:23], v[22:23], v[24:25]
	v_pk_mul_f32 v[24:25], v[36:37], v[26:27]
	v_cvt_pk_bf16_f32 v22, v22, v23
	v_cvt_pk_bf16_f32 v23, v24, v25
	global_store_dwordx2 v[18:19], v[22:23], off offset:160
	v_and_b32_e32 v26, 0xffff0000, v88
	v_lshlrev_b32_e32 v27, 16, v89
	v_and_b32_e32 v32, 0xffff0000, v89
	v_mul_f32_e32 v26, 0xbfb8aa3b, v26
	v_mul_f32_e32 v27, 0xbfb8aa3b, v27
	v_mul_f32_e32 v32, 0xbfb8aa3b, v32
	v_exp_f32_e32 v26, v26
	v_exp_f32_e32 v27, v27
	v_exp_f32_e32 v32, v32
	v_add_f32_e32 v1, 1.0, v1
	v_add_f32_e32 v33, 1.0, v26
	v_add_f32_e32 v34, 1.0, v27
	v_add_f32_e32 v35, 1.0, v32
	v_rcp_f32_e32 v26, v1
	v_rcp_f32_e32 v27, v33
	v_rcp_f32_e32 v32, v34
	v_rcp_f32_e32 v33, v35
	v_pk_mul_f32 v[28:29], v[28:29], v[0:1] op_sel_hi:[1, 0]
	v_pk_mul_f32 v[30:31], v[30:31], v[0:1] op_sel_hi:[1, 0]
	v_lshlrev_b32_e32 v1, 16, v86
	v_mul_f32_e32 v1, 0xbfb8aa3b, v1
	v_exp_f32_e32 v1, v1
	s_waitcnt vmcnt(15)
	v_pk_mul_f32 v[22:23], v[142:143], v[28:29]
	v_pk_mul_f32 v[24:25], v[144:145], v[30:31]
	v_pk_mul_f32 v[22:23], v[26:27], v[22:23]
	v_pk_mul_f32 v[24:25], v[32:33], v[24:25]
	v_cvt_pk_bf16_f32 v22, v22, v23
	v_cvt_pk_bf16_f32 v23, v24, v25
	global_store_dwordx2 v[18:19], v[22:23], off offset:176
	v_and_b32_e32 v26, 0xffff0000, v86
	v_lshlrev_b32_e32 v27, 16, v87
	v_and_b32_e32 v28, 0xffff0000, v87
	v_mul_f32_e32 v26, 0xbfb8aa3b, v26
	v_mul_f32_e32 v27, 0xbfb8aa3b, v27
	v_mul_f32_e32 v28, 0xbfb8aa3b, v28
	v_exp_f32_e32 v26, v26
	v_exp_f32_e32 v27, v27
	v_exp_f32_e32 v28, v28
	v_add_f32_e32 v1, 1.0, v1
	v_add_f32_e32 v29, 1.0, v26
	v_add_f32_e32 v30, 1.0, v27
	v_add_f32_e32 v31, 1.0, v28
	v_rcp_f32_e32 v26, v1
	v_rcp_f32_e32 v27, v29
	v_rcp_f32_e32 v28, v30
	v_rcp_f32_e32 v29, v31
	v_pk_mul_f32 v[20:21], v[20:21], v[0:1] op_sel_hi:[1, 0]
	v_pk_mul_f32 v[14:15], v[14:15], v[0:1] op_sel_hi:[1, 0]
	v_lshlrev_b32_e32 v1, 16, v84
	v_mul_f32_e32 v1, 0xbfb8aa3b, v1
	v_exp_f32_e32 v1, v1
	s_waitcnt vmcnt(15)
	v_pk_mul_f32 v[20:21], v[146:147], v[20:21]
	v_pk_mul_f32 v[14:15], v[148:149], v[14:15]
	v_pk_mul_f32 v[20:21], v[26:27], v[20:21]
	v_pk_mul_f32 v[14:15], v[28:29], v[14:15]
	v_cvt_pk_bf16_f32 v20, v20, v21
	v_cvt_pk_bf16_f32 v21, v14, v15
	global_store_dwordx2 v[18:19], v[20:21], off offset:192
	v_and_b32_e32 v14, 0xffff0000, v84
	v_lshlrev_b32_e32 v15, 16, v85
	v_and_b32_e32 v24, 0xffff0000, v85
	v_mul_f32_e32 v14, 0xbfb8aa3b, v14
	v_mul_f32_e32 v15, 0xbfb8aa3b, v15
	v_mul_f32_e32 v24, 0xbfb8aa3b, v24
	v_exp_f32_e32 v14, v14
	v_exp_f32_e32 v15, v15
	v_exp_f32_e32 v24, v24
	v_add_f32_e32 v1, 1.0, v1
	v_add_f32_e32 v25, 1.0, v14
	v_add_f32_e32 v26, 1.0, v15
	v_add_f32_e32 v27, 1.0, v24
	v_rcp_f32_e32 v14, v1
	v_rcp_f32_e32 v15, v25
	v_rcp_f32_e32 v24, v26
	v_rcp_f32_e32 v25, v27
	v_pk_mul_f32 v[4:5], v[4:5], v[0:1] op_sel_hi:[1, 0]
	v_pk_mul_f32 v[6:7], v[6:7], v[0:1] op_sel_hi:[1, 0]
	v_lshlrev_b32_e32 v1, 16, v82
	v_mul_f32_e32 v1, 0xbfb8aa3b, v1
	v_exp_f32_e32 v1, v1
	s_waitcnt vmcnt(15)
	v_pk_mul_f32 v[4:5], v[150:151], v[4:5]
	v_pk_mul_f32 v[6:7], v[152:153], v[6:7]
	v_pk_mul_f32 v[4:5], v[14:15], v[4:5]
	v_pk_mul_f32 v[6:7], v[24:25], v[6:7]
	v_cvt_pk_bf16_f32 v4, v4, v5
	v_cvt_pk_bf16_f32 v5, v6, v7
	global_store_dwordx2 v[18:19], v[4:5], off offset:208
	v_and_b32_e32 v14, 0xffff0000, v82
	v_lshlrev_b32_e32 v15, 16, v83
	v_and_b32_e32 v20, 0xffff0000, v83
	v_mul_f32_e32 v14, 0xbfb8aa3b, v14
	v_mul_f32_e32 v15, 0xbfb8aa3b, v15
	v_mul_f32_e32 v20, 0xbfb8aa3b, v20
	v_exp_f32_e32 v14, v14
	v_exp_f32_e32 v15, v15
	v_exp_f32_e32 v20, v20
	v_add_f32_e32 v1, 1.0, v1
	v_add_f32_e32 v21, 1.0, v14
	v_add_f32_e32 v22, 1.0, v15
	v_add_f32_e32 v23, 1.0, v20
	v_rcp_f32_e32 v14, v1
	v_rcp_f32_e32 v15, v21
	v_rcp_f32_e32 v20, v22
	v_rcp_f32_e32 v21, v23
	v_pk_mul_f32 v[8:9], v[8:9], v[0:1] op_sel_hi:[1, 0]
	v_pk_mul_f32 v[16:17], v[16:17], v[0:1] op_sel_hi:[1, 0]
	v_lshlrev_b32_e32 v1, 16, v80
	v_mul_f32_e32 v1, 0xbfb8aa3b, v1
	v_exp_f32_e32 v1, v1
	s_waitcnt vmcnt(15)
	v_pk_mul_f32 v[4:5], v[154:155], v[8:9]
	v_pk_mul_f32 v[6:7], v[156:157], v[16:17]
	v_pk_mul_f32 v[4:5], v[14:15], v[4:5]
	v_pk_mul_f32 v[6:7], v[20:21], v[6:7]
	v_cvt_pk_bf16_f32 v4, v4, v5
	v_cvt_pk_bf16_f32 v5, v6, v7
	global_store_dwordx2 v[18:19], v[4:5], off offset:224
	v_and_b32_e32 v6, 0xffff0000, v80
	v_lshlrev_b32_e32 v7, 16, v81
	v_and_b32_e32 v8, 0xffff0000, v81
	v_mul_f32_e32 v6, 0xbfb8aa3b, v6
	v_mul_f32_e32 v7, 0xbfb8aa3b, v7
	v_mul_f32_e32 v8, 0xbfb8aa3b, v8
	v_exp_f32_e32 v6, v6
	v_exp_f32_e32 v7, v7
	v_exp_f32_e32 v8, v8
	v_add_f32_e32 v1, 1.0, v1
	v_add_f32_e32 v9, 1.0, v6
	v_add_f32_e32 v14, 1.0, v7
	v_add_f32_e32 v15, 1.0, v8
	v_rcp_f32_e32 v6, v1
	v_rcp_f32_e32 v7, v9
	v_rcp_f32_e32 v8, v14
	v_rcp_f32_e32 v9, v15
	v_pk_mul_f32 v[10:11], v[10:11], v[0:1] op_sel_hi:[1, 0]
	v_pk_mul_f32 v[0:1], v[12:13], v[0:1] op_sel_hi:[1, 0]
	s_waitcnt vmcnt(15)
	v_pk_mul_f32 v[2:3], v[158:159], v[10:11]
	v_pk_mul_f32 v[0:1], v[160:161], v[0:1]
	v_pk_mul_f32 v[2:3], v[6:7], v[2:3]
	v_pk_mul_f32 v[0:1], v[8:9], v[0:1]
	v_cvt_pk_bf16_f32 v2, v2, v3
	v_cvt_pk_bf16_f32 v3, v0, v1
	global_store_dwordx2 v[18:19], v[2:3], off offset:240
	s_barrier
	s_cbranch_scc1 .LBB0_119

.LBB0_72:
	s_cmp_lg_u32 s20, 0
	s_cbranch_scc0 .LBB0_107
	v_add_u32_e32 v66, s20, v192
	v_mov_b64_e32 v[64:65], s[10:11]
	s_movk_i32 s0, 0x1c00
	v_mad_i64_i32 v[64:65], s[0:1], v66, s0, v[64:65]
	v_lshl_add_u64 v[64:65], v[162:163], 1, v[64:65]
	v_lshl_add_u64 v[64:65], v[64:65], 0, v[112:113]
	s_mov_b64 s[0:1], 0x1000
	v_lshl_add_u64 v[200:201], v[64:65], 0, s[0:1]
	v_add_co_u32_e32 v64, vcc, 0x1000, v64
	s_nop 0
	v_addc_co_u32_e32 v65, vcc, 0, v65, vcc
	global_load_dwordx4 v[130:133], v[200:201], off
	global_load_dwordx4 v[134:137], v[200:201], off offset:32
	global_load_dwordx4 v[138:141], v[200:201], off offset:64
	global_load_dwordx4 v[142:145], v[200:201], off offset:96
	global_load_dwordx4 v[146:149], v[200:201], off offset:128
	global_load_dwordx4 v[150:153], v[200:201], off offset:160
	global_load_dwordx4 v[154:157], v[200:201], off offset:192
	global_load_dwordx4 v[158:161], v[200:201], off offset:224
	s_waitcnt vmcnt(7)
	v_mfma_f32_32x32x16_bf16 v[64:79], v[130:133], v[96:99], 0
	s_waitcnt vmcnt(6)
	v_mfma_f32_32x32x16_bf16 v[64:79], v[134:137], v[100:103], v[64:79]
	s_waitcnt vmcnt(5)
	v_mfma_f32_32x32x16_bf16 v[64:79], v[138:141], v[104:107], v[64:79]
	s_waitcnt vmcnt(4)
	v_mfma_f32_32x32x16_bf16 v[64:79], v[142:145], v[108:111], v[64:79]
	s_waitcnt vmcnt(3)
	v_mfma_f32_32x32x16_bf16 v[64:79], v[146:149], v[114:117], v[64:79]
	s_waitcnt vmcnt(2)
	v_mfma_f32_32x32x16_bf16 v[64:79], v[150:153], v[118:121], v[64:79]
	s_waitcnt vmcnt(1)
	v_mfma_f32_32x32x16_bf16 v[64:79], v[154:157], v[122:125], v[64:79]
	s_waitcnt vmcnt(0)
	v_mfma_f32_32x32x16_bf16 v[64:79], v[158:161], v[126:129], v[64:79]
	s_cbranch_execnz .LBB0_75

.LBB0_605:
	s_or_b64 exec, exec, s[0:1]
	v_mov_b32_dpp v198, v52 row_shr:2 row_mask:0xf bank_mask:0xf bound_ctrl:1
	v_mov_b32_dpp v196, v52 row_shr:1 row_mask:0xf bank_mask:0xf bound_ctrl:1
	v_mov_b32_dpp v194, v118 row_shr:2 row_mask:0xf bank_mask:0xf bound_ctrl:1
	v_mov_b32_dpp v192, v118 row_shr:1 row_mask:0xf bank_mask:0xf bound_ctrl:1
	v_mov_b32_dpp v199, v53 row_shr:2 row_mask:0xf bank_mask:0xf bound_ctrl:1
	v_mov_b32_dpp v197, v53 row_shr:1 row_mask:0xf bank_mask:0xf bound_ctrl:1
	v_mov_b32_dpp v195, v119 row_shr:2 row_mask:0xf bank_mask:0xf bound_ctrl:1
	v_mov_b32_dpp v193, v119 row_shr:1 row_mask:0xf bank_mask:0xf bound_ctrl:1
	v_mov_b32_dpp v190, v54 row_shr:2 row_mask:0xf bank_mask:0xf bound_ctrl:1
	v_mov_b32_dpp v188, v54 row_shr:1 row_mask:0xf bank_mask:0xf bound_ctrl:1
	v_mov_b32_dpp v186, v120 row_shr:2 row_mask:0xf bank_mask:0xf bound_ctrl:1
	v_mov_b32_dpp v184, v120 row_shr:1 row_mask:0xf bank_mask:0xf bound_ctrl:1
	v_mov_b32_dpp v191, v55 row_shr:2 row_mask:0xf bank_mask:0xf bound_ctrl:1
	v_mov_b32_dpp v189, v55 row_shr:1 row_mask:0xf bank_mask:0xf bound_ctrl:1
	v_mov_b32_dpp v187, v121 row_shr:2 row_mask:0xf bank_mask:0xf bound_ctrl:1
	v_mov_b32_dpp v185, v121 row_shr:1 row_mask:0xf bank_mask:0xf bound_ctrl:1
	v_or_b32_e32 v175, 16, v172
	s_and_saveexec_b64 s[0:1], s[40:41]
	s_cbranch_execz .LBB0_607
	s_nop 0
	v_pk_fma_f32 v[198:199], v[146:147], v[198:199], v[158:159]
	v_pk_fma_f32 v[190:191], v[148:149], v[190:191], v[160:161]
	v_pk_fma_f32 v[196:197], v[150:151], v[196:197], v[198:199]
	v_pk_fma_f32 v[188:189], v[152:153], v[188:189], v[190:191]
	v_pk_fma_f32 v[196:197], v[52:53], v[154:155], v[196:197]
	v_pk_fma_f32 v[188:189], v[54:55], v[156:157], v[188:189]
	v_mul_f32_e32 v173, 0x3dd2d3e8, v196
	v_fmaak_f32 v173, v196, v173, 0x40135761
	v_mul_f32_e32 v198, 0x3dd2d3e8, v197
	v_mul_f32_e32 v173, v196, v173
	v_fmaak_f32 v198, v197, v198, 0x40135761
	v_exp_f32_e32 v173, v173
	v_mul_f32_e32 v198, v197, v198
	v_exp_f32_e32 v199, v198
	v_mul_f32_e32 v190, 0x3dd2d3e8, v189
	v_add_f32_e32 v173, 1.0, v173
	v_rcp_f32_e32 v198, v173
	v_add_f32_e32 v173, 1.0, v199
	v_rcp_f32_e32 v199, v173
	v_mul_f32_e32 v173, 0x3dd2d3e8, v188
	v_fmaak_f32 v173, v188, v173, 0x40135761
	v_mul_f32_e32 v173, v188, v173
	v_fmaak_f32 v190, v189, v190, 0x40135761
	v_pk_fma_f32 v[194:195], v[130:131], v[194:195], v[142:143]
	v_exp_f32_e32 v173, v173
	v_mul_f32_e32 v190, v189, v190
	v_pk_fma_f32 v[192:193], v[134:135], v[192:193], v[194:195]
	v_pk_fma_f32 v[194:195], v[196:197], v[198:199], v[196:197] neg_lo:[1,0,0] neg_hi:[1,0,0]
	v_exp_f32_e32 v196, v190
	v_pk_fma_f32 v[192:193], v[118:119], v[138:139], v[192:193]
	v_add_f32_e32 v173, 1.0, v173
	v_pk_mul_f32 v[190:191], v[192:193], v[194:195]
	v_rcp_f32_e32 v192, v173
	v_add_f32_e32 v173, 1.0, v196
	v_rcp_f32_e32 v193, v173
	v_pk_fma_f32 v[186:187], v[132:133], v[186:187], v[144:145]
	s_nop 0
	v_pk_fma_f32 v[184:185], v[136:137], v[184:185], v[186:187]
	v_pk_fma_f32 v[186:187], v[188:189], v[192:193], v[188:189] neg_lo:[1,0,0] neg_hi:[1,0,0]
	v_pk_fma_f32 v[184:185], v[120:121], v[140:141], v[184:185]
	s_nop 0
	v_pk_mul_f32 v[184:185], v[184:185], v[186:187]
	v_cvt_pk_bf16_f32 v186, v190, v191
	v_cvt_pk_bf16_f32 v187, v184, v185
	v_mad_i64_i32 v[184:185], s[6:7], v175, s5, v[178:179]
	global_store_dwordx2 v[184:185], v[186:187], off
.LBB0_607:
	s_or_b64 exec, exec, s[0:1]
	v_mov_b32_dpp v198, v44 row_shr:2 row_mask:0xf bank_mask:0xf bound_ctrl:1
	v_mov_b32_dpp v196, v44 row_shr:1 row_mask:0xf bank_mask:0xf bound_ctrl:1
	v_mov_b32_dpp v194, v108 row_shr:2 row_mask:0xf bank_mask:0xf bound_ctrl:1
	v_mov_b32_dpp v192, v108 row_shr:1 row_mask:0xf bank_mask:0xf bound_ctrl:1
	v_mov_b32_dpp v199, v45 row_shr:2 row_mask:0xf bank_mask:0xf bound_ctrl:1
	v_mov_b32_dpp v197, v45 row_shr:1 row_mask:0xf bank_mask:0xf bound_ctrl:1
	v_mov_b32_dpp v195, v109 row_shr:2 row_mask:0xf bank_mask:0xf bound_ctrl:1
	v_mov_b32_dpp v193, v109 row_shr:1 row_mask:0xf bank_mask:0xf bound_ctrl:1
	v_mov_b32_dpp v190, v46 row_shr:2 row_mask:0xf bank_mask:0xf bound_ctrl:1
	v_mov_b32_dpp v188, v46 row_shr:1 row_mask:0xf bank_mask:0xf bound_ctrl:1
	v_mov_b32_dpp v186, v110 row_shr:2 row_mask:0xf bank_mask:0xf bound_ctrl:1
	v_mov_b32_dpp v184, v110 row_shr:1 row_mask:0xf bank_mask:0xf bound_ctrl:1
	v_mov_b32_dpp v191, v47 row_shr:2 row_mask:0xf bank_mask:0xf bound_ctrl:1
	v_mov_b32_dpp v189, v47 row_shr:1 row_mask:0xf bank_mask:0xf bound_ctrl:1
	v_mov_b32_dpp v187, v111 row_shr:2 row_mask:0xf bank_mask:0xf bound_ctrl:1
	v_mov_b32_dpp v185, v111 row_shr:1 row_mask:0xf bank_mask:0xf bound_ctrl:1
	v_or_b32_e32 v205, 32, v172
	s_and_saveexec_b64 s[0:1], s[40:41]
	s_cbranch_execz .LBB0_609
	s_nop 0
	v_pk_fma_f32 v[198:199], v[146:147], v[198:199], v[158:159]
	v_pk_fma_f32 v[190:191], v[148:149], v[190:191], v[160:161]
	v_pk_fma_f32 v[196:197], v[150:151], v[196:197], v[198:199]
	v_pk_fma_f32 v[188:189], v[152:153], v[188:189], v[190:191]
	v_pk_fma_f32 v[196:197], v[44:45], v[154:155], v[196:197]
	v_pk_fma_f32 v[188:189], v[46:47], v[156:157], v[188:189]
	v_mul_f32_e32 v173, 0x3dd2d3e8, v196
	v_fmaak_f32 v173, v196, v173, 0x40135761
	v_mul_f32_e32 v198, 0x3dd2d3e8, v197
	v_mul_f32_e32 v173, v196, v173
	v_fmaak_f32 v198, v197, v198, 0x40135761
	v_exp_f32_e32 v173, v173
	v_mul_f32_e32 v198, v197, v198
	v_exp_f32_e32 v199, v198
	v_mul_f32_e32 v190, 0x3dd2d3e8, v189
	v_add_f32_e32 v173, 1.0, v173
	v_rcp_f32_e32 v198, v173
	v_add_f32_e32 v173, 1.0, v199
	v_rcp_f32_e32 v199, v173
	v_mul_f32_e32 v173, 0x3dd2d3e8, v188
	v_fmaak_f32 v173, v188, v173, 0x40135761
	v_mul_f32_e32 v173, v188, v173
	v_fmaak_f32 v190, v189, v190, 0x40135761
	v_pk_fma_f32 v[194:195], v[130:131], v[194:195], v[142:143]
	v_exp_f32_e32 v173, v173
	v_mul_f32_e32 v190, v189, v190
	v_pk_fma_f32 v[192:193], v[134:135], v[192:193], v[194:195]
	v_pk_fma_f32 v[194:195], v[196:197], v[198:199], v[196:197] neg_lo:[1,0,0] neg_hi:[1,0,0]
	v_exp_f32_e32 v196, v190
	v_pk_fma_f32 v[192:193], v[108:109], v[138:139], v[192:193]
	v_add_f32_e32 v173, 1.0, v173
	v_pk_mul_f32 v[190:191], v[192:193], v[194:195]
	v_rcp_f32_e32 v192, v173
	v_add_f32_e32 v173, 1.0, v196
	v_rcp_f32_e32 v193, v173
	v_pk_fma_f32 v[186:187], v[132:133], v[186:187], v[144:145]
	s_nop 0
	v_pk_fma_f32 v[184:185], v[136:137], v[184:185], v[186:187]
	v_pk_fma_f32 v[186:187], v[188:189], v[192:193], v[188:189] neg_lo:[1,0,0] neg_hi:[1,0,0]
	v_pk_fma_f32 v[184:185], v[110:111], v[140:141], v[184:185]
	s_nop 0
	v_pk_mul_f32 v[184:185], v[184:185], v[186:187]
	v_cvt_pk_bf16_f32 v186, v190, v191
	v_cvt_pk_bf16_f32 v187, v184, v185
	v_mad_i64_i32 v[184:185], s[6:7], v205, s5, v[178:179]
	global_store_dwordx2 v[184:185], v[186:187], off
.LBB0_609:
	s_or_b64 exec, exec, s[0:1]
	v_mov_b32_dpp v198, v36 row_shr:2 row_mask:0xf bank_mask:0xf bound_ctrl:1
	v_mov_b32_dpp v196, v36 row_shr:1 row_mask:0xf bank_mask:0xf bound_ctrl:1
	v_mov_b32_dpp v194, v100 row_shr:2 row_mask:0xf bank_mask:0xf bound_ctrl:1
	v_mov_b32_dpp v192, v100 row_shr:1 row_mask:0xf bank_mask:0xf bound_ctrl:1
	v_mov_b32_dpp v199, v37 row_shr:2 row_mask:0xf bank_mask:0xf bound_ctrl:1
	v_mov_b32_dpp v197, v37 row_shr:1 row_mask:0xf bank_mask:0xf bound_ctrl:1
	v_mov_b32_dpp v195, v101 row_shr:2 row_mask:0xf bank_mask:0xf bound_ctrl:1
	v_mov_b32_dpp v193, v101 row_shr:1 row_mask:0xf bank_mask:0xf bound_ctrl:1
	v_mov_b32_dpp v190, v38 row_shr:2 row_mask:0xf bank_mask:0xf bound_ctrl:1
	v_mov_b32_dpp v188, v38 row_shr:1 row_mask:0xf bank_mask:0xf bound_ctrl:1
	v_mov_b32_dpp v186, v102 row_shr:2 row_mask:0xf bank_mask:0xf bound_ctrl:1
	v_mov_b32_dpp v184, v102 row_shr:1 row_mask:0xf bank_mask:0xf bound_ctrl:1
	v_mov_b32_dpp v191, v39 row_shr:2 row_mask:0xf bank_mask:0xf bound_ctrl:1
	v_mov_b32_dpp v189, v39 row_shr:1 row_mask:0xf bank_mask:0xf bound_ctrl:1
	v_mov_b32_dpp v187, v103 row_shr:2 row_mask:0xf bank_mask:0xf bound_ctrl:1
	v_mov_b32_dpp v185, v103 row_shr:1 row_mask:0xf bank_mask:0xf bound_ctrl:1
	v_or_b32_e32 v206, 48, v172
	s_and_saveexec_b64 s[0:1], s[40:41]
	s_cbranch_execz .LBB0_611
	s_nop 0
	v_pk_fma_f32 v[198:199], v[146:147], v[198:199], v[158:159]
	v_pk_fma_f32 v[190:191], v[148:149], v[190:191], v[160:161]
	v_pk_fma_f32 v[196:197], v[150:151], v[196:197], v[198:199]
	v_pk_fma_f32 v[188:189], v[152:153], v[188:189], v[190:191]
	v_pk_fma_f32 v[196:197], v[36:37], v[154:155], v[196:197]
	v_pk_fma_f32 v[188:189], v[38:39], v[156:157], v[188:189]
	v_mul_f32_e32 v173, 0x3dd2d3e8, v196
	v_fmaak_f32 v173, v196, v173, 0x40135761
	v_mul_f32_e32 v198, 0x3dd2d3e8, v197
	v_mul_f32_e32 v173, v196, v173
	v_fmaak_f32 v198, v197, v198, 0x40135761
	v_exp_f32_e32 v173, v173
	v_mul_f32_e32 v198, v197, v198
	v_exp_f32_e32 v199, v198
	v_mul_f32_e32 v190, 0x3dd2d3e8, v189
	v_add_f32_e32 v173, 1.0, v173
	v_rcp_f32_e32 v198, v173
	v_add_f32_e32 v173, 1.0, v199
	v_rcp_f32_e32 v199, v173
	v_mul_f32_e32 v173, 0x3dd2d3e8, v188
	v_fmaak_f32 v173, v188, v173, 0x40135761
	v_mul_f32_e32 v173, v188, v173
	v_fmaak_f32 v190, v189, v190, 0x40135761
	v_pk_fma_f32 v[194:195], v[130:131], v[194:195], v[142:143]
	v_exp_f32_e32 v173, v173
	v_mul_f32_e32 v190, v189, v190
	v_pk_fma_f32 v[192:193], v[134:135], v[192:193], v[194:195]
	v_pk_fma_f32 v[194:195], v[196:197], v[198:199], v[196:197] neg_lo:[1,0,0] neg_hi:[1,0,0]
	v_exp_f32_e32 v196, v190
	v_pk_fma_f32 v[192:193], v[100:101], v[138:139], v[192:193]
	v_add_f32_e32 v173, 1.0, v173
	v_pk_mul_f32 v[190:191], v[192:193], v[194:195]
	v_rcp_f32_e32 v192, v173
	v_add_f32_e32 v173, 1.0, v196
	v_rcp_f32_e32 v193, v173
	v_pk_fma_f32 v[186:187], v[132:133], v[186:187], v[144:145]
	s_nop 0
	v_pk_fma_f32 v[184:185], v[136:137], v[184:185], v[186:187]
	v_pk_fma_f32 v[186:187], v[188:189], v[192:193], v[188:189] neg_lo:[1,0,0] neg_hi:[1,0,0]
	v_pk_fma_f32 v[184:185], v[102:103], v[140:141], v[184:185]
	s_nop 0
	v_pk_mul_f32 v[184:185], v[184:185], v[186:187]
	v_cvt_pk_bf16_f32 v186, v190, v191
	v_cvt_pk_bf16_f32 v187, v184, v185
	v_mad_i64_i32 v[184:185], s[6:7], v206, s5, v[178:179]
	global_store_dwordx2 v[184:185], v[186:187], off
.LBB0_611:
	s_or_b64 exec, exec, s[0:1]
	v_add_u32_e32 v173, 0x80, v172
	v_mov_b32_dpp v198, v28 row_shr:2 row_mask:0xf bank_mask:0xf bound_ctrl:1
	v_mov_b32_dpp v196, v28 row_shr:1 row_mask:0xf bank_mask:0xf bound_ctrl:1
	v_mov_b32_dpp v194, v92 row_shr:2 row_mask:0xf bank_mask:0xf bound_ctrl:1
	v_mov_b32_dpp v192, v92 row_shr:1 row_mask:0xf bank_mask:0xf bound_ctrl:1
	v_mov_b32_dpp v199, v29 row_shr:2 row_mask:0xf bank_mask:0xf bound_ctrl:1
	v_mov_b32_dpp v197, v29 row_shr:1 row_mask:0xf bank_mask:0xf bound_ctrl:1
	v_mov_b32_dpp v195, v93 row_shr:2 row_mask:0xf bank_mask:0xf bound_ctrl:1
	v_mov_b32_dpp v193, v93 row_shr:1 row_mask:0xf bank_mask:0xf bound_ctrl:1
	v_mov_b32_dpp v190, v30 row_shr:2 row_mask:0xf bank_mask:0xf bound_ctrl:1
	v_mov_b32_dpp v188, v30 row_shr:1 row_mask:0xf bank_mask:0xf bound_ctrl:1
	v_mov_b32_dpp v186, v94 row_shr:2 row_mask:0xf bank_mask:0xf bound_ctrl:1
	v_mov_b32_dpp v184, v94 row_shr:1 row_mask:0xf bank_mask:0xf bound_ctrl:1
	v_mov_b32_dpp v191, v31 row_shr:2 row_mask:0xf bank_mask:0xf bound_ctrl:1
	v_mov_b32_dpp v189, v31 row_shr:1 row_mask:0xf bank_mask:0xf bound_ctrl:1
	v_mov_b32_dpp v187, v95 row_shr:2 row_mask:0xf bank_mask:0xf bound_ctrl:1
	v_mov_b32_dpp v185, v95 row_shr:1 row_mask:0xf bank_mask:0xf bound_ctrl:1
	s_and_saveexec_b64 s[0:1], s[40:41]
	s_cbranch_execz .LBB0_613
	s_nop 0
	v_pk_fma_f32 v[198:199], v[146:147], v[198:199], v[158:159]
	v_pk_fma_f32 v[190:191], v[148:149], v[190:191], v[160:161]
	v_pk_fma_f32 v[196:197], v[150:151], v[196:197], v[198:199]
	v_pk_fma_f32 v[188:189], v[152:153], v[188:189], v[190:191]
	v_pk_fma_f32 v[196:197], v[28:29], v[154:155], v[196:197]
	v_pk_fma_f32 v[188:189], v[30:31], v[156:157], v[188:189]
	v_mul_f32_e32 v198, 0x3dd2d3e8, v196
	v_mul_f32_e32 v199, 0x3dd2d3e8, v197
	v_fmaak_f32 v198, v196, v198, 0x40135761
	v_fmaak_f32 v199, v197, v199, 0x40135761
	v_mul_f32_e32 v198, v196, v198
	v_mul_f32_e32 v199, v197, v199
	v_exp_f32_e32 v198, v198
	v_exp_f32_e32 v199, v199
	v_mul_f32_e32 v190, 0x3dd2d3e8, v188
	v_fmaak_f32 v190, v188, v190, 0x40135761
	v_add_f32_e32 v198, 1.0, v198
	v_add_f32_e32 v199, 1.0, v199
	v_rcp_f32_e32 v198, v198
	v_rcp_f32_e32 v199, v199
	v_pk_fma_f32 v[194:195], v[130:131], v[194:195], v[142:143]
	v_mul_f32_e32 v190, v188, v190
	v_pk_fma_f32 v[192:193], v[134:135], v[192:193], v[194:195]
	v_pk_fma_f32 v[194:195], v[196:197], v[198:199], v[196:197] neg_lo:[1,0,0] neg_hi:[1,0,0]
	v_exp_f32_e32 v196, v190
	v_mul_f32_e32 v190, 0x3dd2d3e8, v189
	v_fmaak_f32 v190, v189, v190, 0x40135761
	v_mul_f32_e32 v190, v189, v190
	v_exp_f32_e32 v197, v190
	v_pk_fma_f32 v[192:193], v[92:93], v[138:139], v[192:193]
	v_pk_fma_f32 v[186:187], v[132:133], v[186:187], v[144:145]
	v_pk_mul_f32 v[190:191], v[192:193], v[194:195]
	v_add_f32_e32 v192, 1.0, v196
	v_add_f32_e32 v193, 1.0, v197
	v_rcp_f32_e32 v192, v192
	v_rcp_f32_e32 v193, v193
	v_pk_fma_f32 v[184:185], v[136:137], v[184:185], v[186:187]
	v_pk_fma_f32 v[186:187], v[188:189], v[192:193], v[188:189] neg_lo:[1,0,0] neg_hi:[1,0,0]
	v_pk_fma_f32 v[184:185], v[94:95], v[140:141], v[184:185]
	s_nop 0
	v_pk_mul_f32 v[184:185], v[184:185], v[186:187]
	v_cvt_pk_bf16_f32 v186, v190, v191
	v_cvt_pk_bf16_f32 v187, v184, v185
	v_mad_i64_i32 v[184:185], s[6:7], v173, s5, v[178:179]
	global_store_dwordx2 v[184:185], v[186:187], off
.LBB0_613:
	s_or_b64 exec, exec, s[0:1]
	v_mov_b32_dpp v198, v20 row_shr:2 row_mask:0xf bank_mask:0xf bound_ctrl:1
	v_mov_b32_dpp v196, v20 row_shr:1 row_mask:0xf bank_mask:0xf bound_ctrl:1
	v_mov_b32_dpp v194, v84 row_shr:2 row_mask:0xf bank_mask:0xf bound_ctrl:1
	v_mov_b32_dpp v192, v84 row_shr:1 row_mask:0xf bank_mask:0xf bound_ctrl:1
	v_mov_b32_dpp v199, v21 row_shr:2 row_mask:0xf bank_mask:0xf bound_ctrl:1
	v_mov_b32_dpp v197, v21 row_shr:1 row_mask:0xf bank_mask:0xf bound_ctrl:1
	v_mov_b32_dpp v195, v85 row_shr:2 row_mask:0xf bank_mask:0xf bound_ctrl:1
	v_mov_b32_dpp v193, v85 row_shr:1 row_mask:0xf bank_mask:0xf bound_ctrl:1
	v_mov_b32_dpp v190, v22 row_shr:2 row_mask:0xf bank_mask:0xf bound_ctrl:1
	v_mov_b32_dpp v188, v22 row_shr:1 row_mask:0xf bank_mask:0xf bound_ctrl:1
	v_mov_b32_dpp v186, v86 row_shr:2 row_mask:0xf bank_mask:0xf bound_ctrl:1
	v_mov_b32_dpp v184, v86 row_shr:1 row_mask:0xf bank_mask:0xf bound_ctrl:1
	v_mov_b32_dpp v191, v23 row_shr:2 row_mask:0xf bank_mask:0xf bound_ctrl:1
	v_mov_b32_dpp v189, v23 row_shr:1 row_mask:0xf bank_mask:0xf bound_ctrl:1
	v_mov_b32_dpp v187, v87 row_shr:2 row_mask:0xf bank_mask:0xf bound_ctrl:1
	v_mov_b32_dpp v185, v87 row_shr:1 row_mask:0xf bank_mask:0xf bound_ctrl:1
	v_add_u32_e32 v207, 0x90, v172
	s_and_saveexec_b64 s[0:1], s[40:41]
	s_cbranch_execz .LBB0_615
	s_nop 0
	v_pk_fma_f32 v[198:199], v[146:147], v[198:199], v[158:159]
	v_pk_fma_f32 v[190:191], v[148:149], v[190:191], v[160:161]
	v_pk_fma_f32 v[196:197], v[150:151], v[196:197], v[198:199]
	v_pk_fma_f32 v[188:189], v[152:153], v[188:189], v[190:191]
	v_pk_fma_f32 v[196:197], v[20:21], v[154:155], v[196:197]
	v_pk_fma_f32 v[188:189], v[22:23], v[156:157], v[188:189]
	v_mul_f32_e32 v198, 0x3dd2d3e8, v196
	v_mul_f32_e32 v199, 0x3dd2d3e8, v197
	v_fmaak_f32 v198, v196, v198, 0x40135761
	v_fmaak_f32 v199, v197, v199, 0x40135761
	v_mul_f32_e32 v198, v196, v198
	v_mul_f32_e32 v199, v197, v199
	v_exp_f32_e32 v198, v198
	v_exp_f32_e32 v199, v199
	v_mul_f32_e32 v190, 0x3dd2d3e8, v188
	v_fmaak_f32 v190, v188, v190, 0x40135761
	v_add_f32_e32 v198, 1.0, v198
	v_add_f32_e32 v199, 1.0, v199
	v_rcp_f32_e32 v198, v198
	v_rcp_f32_e32 v199, v199
	v_pk_fma_f32 v[194:195], v[130:131], v[194:195], v[142:143]
	v_mul_f32_e32 v190, v188, v190
	v_pk_fma_f32 v[192:193], v[134:135], v[192:193], v[194:195]
	v_pk_fma_f32 v[194:195], v[196:197], v[198:199], v[196:197] neg_lo:[1,0,0] neg_hi:[1,0,0]
	v_exp_f32_e32 v196, v190
	v_mul_f32_e32 v190, 0x3dd2d3e8, v189
	v_fmaak_f32 v190, v189, v190, 0x40135761
	v_mul_f32_e32 v190, v189, v190
	v_exp_f32_e32 v197, v190
	v_pk_fma_f32 v[192:193], v[84:85], v[138:139], v[192:193]
	v_pk_fma_f32 v[186:187], v[132:133], v[186:187], v[144:145]
	v_pk_mul_f32 v[190:191], v[192:193], v[194:195]
	v_add_f32_e32 v192, 1.0, v196
	v_add_f32_e32 v193, 1.0, v197
	v_rcp_f32_e32 v192, v192
	v_rcp_f32_e32 v193, v193
	v_pk_fma_f32 v[184:185], v[136:137], v[184:185], v[186:187]
	v_pk_fma_f32 v[186:187], v[188:189], v[192:193], v[188:189] neg_lo:[1,0,0] neg_hi:[1,0,0]
	v_pk_fma_f32 v[184:185], v[86:87], v[140:141], v[184:185]
	s_nop 0
	v_pk_mul_f32 v[184:185], v[184:185], v[186:187]
	v_cvt_pk_bf16_f32 v186, v190, v191
	v_cvt_pk_bf16_f32 v187, v184, v185
	v_mad_i64_i32 v[184:185], s[6:7], v207, s5, v[178:179]
	global_store_dwordx2 v[184:185], v[186:187], off
.LBB0_615:
	s_or_b64 exec, exec, s[0:1]
	v_mov_b32_dpp v198, v12 row_shr:2 row_mask:0xf bank_mask:0xf bound_ctrl:1
	v_mov_b32_dpp v196, v12 row_shr:1 row_mask:0xf bank_mask:0xf bound_ctrl:1
	v_mov_b32_dpp v194, v76 row_shr:2 row_mask:0xf bank_mask:0xf bound_ctrl:1
	v_mov_b32_dpp v192, v76 row_shr:1 row_mask:0xf bank_mask:0xf bound_ctrl:1
	v_mov_b32_dpp v199, v13 row_shr:2 row_mask:0xf bank_mask:0xf bound_ctrl:1
	v_mov_b32_dpp v197, v13 row_shr:1 row_mask:0xf bank_mask:0xf bound_ctrl:1
	v_mov_b32_dpp v195, v77 row_shr:2 row_mask:0xf bank_mask:0xf bound_ctrl:1
	v_mov_b32_dpp v193, v77 row_shr:1 row_mask:0xf bank_mask:0xf bound_ctrl:1
	v_mov_b32_dpp v190, v14 row_shr:2 row_mask:0xf bank_mask:0xf bound_ctrl:1
	v_mov_b32_dpp v188, v14 row_shr:1 row_mask:0xf bank_mask:0xf bound_ctrl:1
	v_mov_b32_dpp v186, v78 row_shr:2 row_mask:0xf bank_mask:0xf bound_ctrl:1
	v_mov_b32_dpp v184, v78 row_shr:1 row_mask:0xf bank_mask:0xf bound_ctrl:1
	v_mov_b32_dpp v191, v15 row_shr:2 row_mask:0xf bank_mask:0xf bound_ctrl:1
	v_mov_b32_dpp v189, v15 row_shr:1 row_mask:0xf bank_mask:0xf bound_ctrl:1
	v_mov_b32_dpp v187, v79 row_shr:2 row_mask:0xf bank_mask:0xf bound_ctrl:1
	v_mov_b32_dpp v185, v79 row_shr:1 row_mask:0xf bank_mask:0xf bound_ctrl:1
	v_add_u32_e32 v208, 0xa0, v172
	s_and_saveexec_b64 s[0:1], s[40:41]
	s_cbranch_execz .LBB0_617
	s_nop 0
	v_pk_fma_f32 v[198:199], v[146:147], v[198:199], v[158:159]
	v_pk_fma_f32 v[190:191], v[148:149], v[190:191], v[160:161]
	v_pk_fma_f32 v[196:197], v[150:151], v[196:197], v[198:199]
	v_pk_fma_f32 v[188:189], v[152:153], v[188:189], v[190:191]
	v_pk_fma_f32 v[196:197], v[12:13], v[154:155], v[196:197]
	v_pk_fma_f32 v[188:189], v[14:15], v[156:157], v[188:189]
	v_mul_f32_e32 v198, 0x3dd2d3e8, v196
	v_mul_f32_e32 v199, 0x3dd2d3e8, v197
	v_fmaak_f32 v198, v196, v198, 0x40135761
	v_fmaak_f32 v199, v197, v199, 0x40135761
	v_mul_f32_e32 v198, v196, v198
	v_mul_f32_e32 v199, v197, v199
	v_exp_f32_e32 v198, v198
	v_exp_f32_e32 v199, v199
	v_mul_f32_e32 v190, 0x3dd2d3e8, v188
	v_fmaak_f32 v190, v188, v190, 0x40135761
	v_add_f32_e32 v198, 1.0, v198
	v_add_f32_e32 v199, 1.0, v199
	v_rcp_f32_e32 v198, v198
	v_rcp_f32_e32 v199, v199
	v_pk_fma_f32 v[194:195], v[130:131], v[194:195], v[142:143]
	v_mul_f32_e32 v190, v188, v190
	v_pk_fma_f32 v[192:193], v[134:135], v[192:193], v[194:195]
	v_pk_fma_f32 v[194:195], v[196:197], v[198:199], v[196:197] neg_lo:[1,0,0] neg_hi:[1,0,0]
	v_exp_f32_e32 v196, v190
	v_mul_f32_e32 v190, 0x3dd2d3e8, v189
	v_fmaak_f32 v190, v189, v190, 0x40135761
	v_mul_f32_e32 v190, v189, v190
	v_exp_f32_e32 v197, v190
	v_pk_fma_f32 v[192:193], v[76:77], v[138:139], v[192:193]
	v_pk_fma_f32 v[186:187], v[132:133], v[186:187], v[144:145]
	v_pk_mul_f32 v[190:191], v[192:193], v[194:195]
	v_add_f32_e32 v192, 1.0, v196
	v_add_f32_e32 v193, 1.0, v197
	v_rcp_f32_e32 v192, v192
	v_rcp_f32_e32 v193, v193
	v_pk_fma_f32 v[184:185], v[136:137], v[184:185], v[186:187]
	v_pk_fma_f32 v[186:187], v[188:189], v[192:193], v[188:189] neg_lo:[1,0,0] neg_hi:[1,0,0]
	v_pk_fma_f32 v[184:185], v[78:79], v[140:141], v[184:185]
	s_nop 0
	v_pk_mul_f32 v[184:185], v[184:185], v[186:187]
	v_cvt_pk_bf16_f32 v186, v190, v191
	v_cvt_pk_bf16_f32 v187, v184, v185
	v_mad_i64_i32 v[184:185], s[6:7], v208, s5, v[178:179]
	global_store_dwordx2 v[184:185], v[186:187], off
.LBB0_617:
	s_or_b64 exec, exec, s[0:1]
	v_mov_b32_dpp v198, v4 row_shr:2 row_mask:0xf bank_mask:0xf bound_ctrl:1
	v_mov_b32_dpp v196, v4 row_shr:1 row_mask:0xf bank_mask:0xf bound_ctrl:1
	v_mov_b32_dpp v194, v64 row_shr:2 row_mask:0xf bank_mask:0xf bound_ctrl:1
	v_mov_b32_dpp v192, v64 row_shr:1 row_mask:0xf bank_mask:0xf bound_ctrl:1
	v_mov_b32_dpp v199, v5 row_shr:2 row_mask:0xf bank_mask:0xf bound_ctrl:1
	v_mov_b32_dpp v197, v5 row_shr:1 row_mask:0xf bank_mask:0xf bound_ctrl:1
	v_mov_b32_dpp v195, v65 row_shr:2 row_mask:0xf bank_mask:0xf bound_ctrl:1
	v_mov_b32_dpp v193, v65 row_shr:1 row_mask:0xf bank_mask:0xf bound_ctrl:1
	v_mov_b32_dpp v190, v6 row_shr:2 row_mask:0xf bank_mask:0xf bound_ctrl:1
	v_mov_b32_dpp v188, v6 row_shr:1 row_mask:0xf bank_mask:0xf bound_ctrl:1
	v_mov_b32_dpp v186, v66 row_shr:2 row_mask:0xf bank_mask:0xf bound_ctrl:1
	v_mov_b32_dpp v184, v66 row_shr:1 row_mask:0xf bank_mask:0xf bound_ctrl:1
	v_mov_b32_dpp v191, v7 row_shr:2 row_mask:0xf bank_mask:0xf bound_ctrl:1
	v_mov_b32_dpp v189, v7 row_shr:1 row_mask:0xf bank_mask:0xf bound_ctrl:1
	v_mov_b32_dpp v187, v67 row_shr:2 row_mask:0xf bank_mask:0xf bound_ctrl:1
	v_mov_b32_dpp v185, v67 row_shr:1 row_mask:0xf bank_mask:0xf bound_ctrl:1
	v_add_u32_e32 v209, 0xb0, v172
	s_and_saveexec_b64 s[0:1], s[40:41]
	s_cbranch_execz .LBB0_619
	s_nop 0
	v_pk_fma_f32 v[146:147], v[146:147], v[198:199], v[158:159]
	v_pk_fma_f32 v[130:131], v[130:131], v[194:195], v[142:143]
	v_pk_fma_f32 v[146:147], v[150:151], v[196:197], v[146:147]
	v_pk_fma_f32 v[130:131], v[134:135], v[192:193], v[130:131]
	v_pk_fma_f32 v[146:147], v[4:5], v[154:155], v[146:147]
	v_pk_fma_f32 v[130:131], v[64:65], v[138:139], v[130:131]
	v_mul_f32_e32 v150, 0x3dd2d3e8, v146
	v_mul_f32_e32 v151, 0x3dd2d3e8, v147
	v_fmaak_f32 v150, v146, v150, 0x40135761
	v_fmaak_f32 v151, v147, v151, 0x40135761
	v_mul_f32_e32 v150, v146, v150
	v_mul_f32_e32 v151, v147, v151
	v_exp_f32_e32 v150, v150
	v_exp_f32_e32 v151, v151
	v_pk_fma_f32 v[138:139], v[148:149], v[190:191], v[160:161]
	v_pk_fma_f32 v[132:133], v[132:133], v[186:187], v[144:145]
	v_pk_fma_f32 v[138:139], v[152:153], v[188:189], v[138:139]
	v_add_f32_e32 v150, 1.0, v150
	v_pk_fma_f32 v[138:139], v[6:7], v[156:157], v[138:139]
	v_add_f32_e32 v151, 1.0, v151
	v_mul_f32_e32 v142, 0x3dd2d3e8, v138
	v_mul_f32_e32 v143, 0x3dd2d3e8, v139
	v_fmaak_f32 v142, v138, v142, 0x40135761
	v_fmaak_f32 v143, v139, v143, 0x40135761
	v_rcp_f32_e32 v150, v150
	v_rcp_f32_e32 v151, v151
	v_mul_f32_e32 v142, v138, v142
	v_mul_f32_e32 v143, v139, v143
	v_exp_f32_e32 v142, v142
	v_exp_f32_e32 v143, v143
	v_pk_fma_f32 v[134:135], v[146:147], v[150:151], v[146:147] neg_lo:[1,0,0] neg_hi:[1,0,0]
	v_pk_fma_f32 v[132:133], v[136:137], v[184:185], v[132:133]
	v_pk_mul_f32 v[130:131], v[130:131], v[134:135]
	v_add_f32_e32 v134, 1.0, v142
	v_add_f32_e32 v135, 1.0, v143
	v_rcp_f32_e32 v134, v134
	v_rcp_f32_e32 v135, v135
	v_pk_fma_f32 v[132:133], v[66:67], v[140:141], v[132:133]
	v_cvt_pk_bf16_f32 v130, v130, v131
	v_pk_fma_f32 v[134:135], v[138:139], v[134:135], v[138:139] neg_lo:[1,0,0] neg_hi:[1,0,0]
	s_nop 0
	v_pk_mul_f32 v[132:133], v[132:133], v[134:135]
	s_nop 0
	v_cvt_pk_bf16_f32 v131, v132, v133
	v_mad_i64_i32 v[132:133], s[6:7], v209, s5, v[178:179]
	global_store_dwordx2 v[132:133], v[130:131], off

.LBB0_621:
	s_or_b64 exec, exec, s[0:1]
	v_mov_b32_dpp v194, v48 row_shr:2 row_mask:0xf bank_mask:0xf bound_ctrl:1
	v_mov_b32_dpp v192, v48 row_shr:1 row_mask:0xf bank_mask:0xf bound_ctrl:1
	v_mov_b32_dpp v190, v114 row_shr:2 row_mask:0xf bank_mask:0xf bound_ctrl:1
	v_mov_b32_dpp v188, v114 row_shr:1 row_mask:0xf bank_mask:0xf bound_ctrl:1
	v_mov_b32_dpp v195, v49 row_shr:2 row_mask:0xf bank_mask:0xf bound_ctrl:1
	v_mov_b32_dpp v193, v49 row_shr:1 row_mask:0xf bank_mask:0xf bound_ctrl:1
	v_mov_b32_dpp v191, v115 row_shr:2 row_mask:0xf bank_mask:0xf bound_ctrl:1
	v_mov_b32_dpp v189, v115 row_shr:1 row_mask:0xf bank_mask:0xf bound_ctrl:1
	v_mov_b32_dpp v186, v50 row_shr:2 row_mask:0xf bank_mask:0xf bound_ctrl:1
	v_mov_b32_dpp v184, v50 row_shr:1 row_mask:0xf bank_mask:0xf bound_ctrl:1
	v_mov_b32_dpp v182, v116 row_shr:2 row_mask:0xf bank_mask:0xf bound_ctrl:1
	v_mov_b32_dpp v180, v116 row_shr:1 row_mask:0xf bank_mask:0xf bound_ctrl:1
	v_mov_b32_dpp v187, v51 row_shr:2 row_mask:0xf bank_mask:0xf bound_ctrl:1
	v_mov_b32_dpp v185, v51 row_shr:1 row_mask:0xf bank_mask:0xf bound_ctrl:1
	v_mov_b32_dpp v183, v117 row_shr:2 row_mask:0xf bank_mask:0xf bound_ctrl:1
	v_mov_b32_dpp v181, v117 row_shr:1 row_mask:0xf bank_mask:0xf bound_ctrl:1
	s_and_saveexec_b64 s[0:1], s[40:41]
	s_cbranch_execz .LBB0_623
	s_nop 0
	v_pk_fma_f32 v[194:195], v[146:147], v[194:195], v[158:159]
	v_pk_fma_f32 v[186:187], v[148:149], v[186:187], v[160:161]
	v_pk_fma_f32 v[192:193], v[150:151], v[192:193], v[194:195]
	v_pk_fma_f32 v[184:185], v[152:153], v[184:185], v[186:187]
	v_pk_fma_f32 v[192:193], v[48:49], v[154:155], v[192:193]
	v_pk_fma_f32 v[184:185], v[50:51], v[156:157], v[184:185]
	v_mul_f32_e32 v194, 0x3dd2d3e8, v192
	v_mul_f32_e32 v195, 0x3dd2d3e8, v193
	v_fmaak_f32 v194, v192, v194, 0x40135761
	v_fmaak_f32 v195, v193, v195, 0x40135761
	v_mul_f32_e32 v194, v192, v194
	v_mul_f32_e32 v195, v193, v195
	v_exp_f32_e32 v194, v194
	v_exp_f32_e32 v195, v195
	v_mul_f32_e32 v186, 0x3dd2d3e8, v184
	v_fmaak_f32 v186, v184, v186, 0x40135761
	v_add_f32_e32 v194, 1.0, v194
	v_add_f32_e32 v195, 1.0, v195
	v_rcp_f32_e32 v194, v194
	v_rcp_f32_e32 v195, v195
	s_nop 0
	v_pk_fma_f32 v[190:191], v[130:131], v[190:191], v[142:143]
	v_mul_f32_e32 v186, v184, v186
	v_pk_fma_f32 v[188:189], v[134:135], v[188:189], v[190:191]
	v_pk_fma_f32 v[190:191], v[192:193], v[194:195], v[192:193] neg_lo:[1,0,0] neg_hi:[1,0,0]
	v_exp_f32_e32 v192, v186
	v_mul_f32_e32 v186, 0x3dd2d3e8, v185
	v_fmaak_f32 v186, v185, v186, 0x40135761
	v_mul_f32_e32 v186, v185, v186
	v_exp_f32_e32 v193, v186
	v_pk_fma_f32 v[188:189], v[114:115], v[138:139], v[188:189]
	v_pk_fma_f32 v[182:183], v[132:133], v[182:183], v[144:145]
	v_pk_mul_f32 v[186:187], v[188:189], v[190:191]
	v_add_f32_e32 v188, 1.0, v192
	v_add_f32_e32 v189, 1.0, v193
	v_rcp_f32_e32 v188, v188
	v_rcp_f32_e32 v189, v189
	v_pk_fma_f32 v[180:181], v[136:137], v[180:181], v[182:183]
	v_pk_fma_f32 v[182:183], v[184:185], v[188:189], v[184:185] neg_lo:[1,0,0] neg_hi:[1,0,0]
	v_pk_fma_f32 v[180:181], v[116:117], v[140:141], v[180:181]
	s_nop 0
	v_pk_mul_f32 v[180:181], v[180:181], v[182:183]
	v_cvt_pk_bf16_f32 v182, v186, v187
	v_cvt_pk_bf16_f32 v183, v180, v181
	v_mad_i64_i32 v[180:181], s[6:7], v175, s5, v[178:179]
	global_store_dwordx2 v[180:181], v[182:183], off offset:8
.LBB0_623:
	s_or_b64 exec, exec, s[0:1]
	v_mov_b32_dpp v194, v40 row_shr:2 row_mask:0xf bank_mask:0xf bound_ctrl:1
	v_mov_b32_dpp v192, v40 row_shr:1 row_mask:0xf bank_mask:0xf bound_ctrl:1
	v_mov_b32_dpp v190, v104 row_shr:2 row_mask:0xf bank_mask:0xf bound_ctrl:1
	v_mov_b32_dpp v188, v104 row_shr:1 row_mask:0xf bank_mask:0xf bound_ctrl:1
	v_mov_b32_dpp v195, v41 row_shr:2 row_mask:0xf bank_mask:0xf bound_ctrl:1
	v_mov_b32_dpp v193, v41 row_shr:1 row_mask:0xf bank_mask:0xf bound_ctrl:1
	v_mov_b32_dpp v191, v105 row_shr:2 row_mask:0xf bank_mask:0xf bound_ctrl:1
	v_mov_b32_dpp v189, v105 row_shr:1 row_mask:0xf bank_mask:0xf bound_ctrl:1
	v_mov_b32_dpp v186, v42 row_shr:2 row_mask:0xf bank_mask:0xf bound_ctrl:1
	v_mov_b32_dpp v184, v42 row_shr:1 row_mask:0xf bank_mask:0xf bound_ctrl:1
	v_mov_b32_dpp v182, v106 row_shr:2 row_mask:0xf bank_mask:0xf bound_ctrl:1
	v_mov_b32_dpp v180, v106 row_shr:1 row_mask:0xf bank_mask:0xf bound_ctrl:1
	v_mov_b32_dpp v187, v43 row_shr:2 row_mask:0xf bank_mask:0xf bound_ctrl:1
	v_mov_b32_dpp v185, v43 row_shr:1 row_mask:0xf bank_mask:0xf bound_ctrl:1
	v_mov_b32_dpp v183, v107 row_shr:2 row_mask:0xf bank_mask:0xf bound_ctrl:1
	v_mov_b32_dpp v181, v107 row_shr:1 row_mask:0xf bank_mask:0xf bound_ctrl:1
	s_and_saveexec_b64 s[0:1], s[40:41]
	s_cbranch_execz .LBB0_625
	s_nop 0
	v_pk_fma_f32 v[194:195], v[146:147], v[194:195], v[158:159]
	v_pk_fma_f32 v[186:187], v[148:149], v[186:187], v[160:161]
	v_pk_fma_f32 v[192:193], v[150:151], v[192:193], v[194:195]
	v_pk_fma_f32 v[184:185], v[152:153], v[184:185], v[186:187]
	v_pk_fma_f32 v[192:193], v[40:41], v[154:155], v[192:193]
	v_pk_fma_f32 v[184:185], v[42:43], v[156:157], v[184:185]
	v_mul_f32_e32 v175, 0x3dd2d3e8, v192
	v_fmaak_f32 v175, v192, v175, 0x40135761
	v_mul_f32_e32 v194, 0x3dd2d3e8, v193
	v_mul_f32_e32 v175, v192, v175
	v_fmaak_f32 v194, v193, v194, 0x40135761
	v_exp_f32_e32 v175, v175
	v_mul_f32_e32 v194, v193, v194
	v_exp_f32_e32 v195, v194
	v_mul_f32_e32 v186, 0x3dd2d3e8, v185
	v_add_f32_e32 v175, 1.0, v175
	v_rcp_f32_e32 v194, v175
	v_add_f32_e32 v175, 1.0, v195
	v_rcp_f32_e32 v195, v175
	v_mul_f32_e32 v175, 0x3dd2d3e8, v184
	v_fmaak_f32 v175, v184, v175, 0x40135761
	v_mul_f32_e32 v175, v184, v175
	v_fmaak_f32 v186, v185, v186, 0x40135761
	s_nop 0
	v_pk_fma_f32 v[190:191], v[130:131], v[190:191], v[142:143]
	v_exp_f32_e32 v175, v175
	v_mul_f32_e32 v186, v185, v186
	v_pk_fma_f32 v[188:189], v[134:135], v[188:189], v[190:191]
	v_pk_fma_f32 v[190:191], v[192:193], v[194:195], v[192:193] neg_lo:[1,0,0] neg_hi:[1,0,0]
	v_exp_f32_e32 v192, v186
	v_pk_fma_f32 v[188:189], v[104:105], v[138:139], v[188:189]
	v_add_f32_e32 v175, 1.0, v175
	v_pk_mul_f32 v[186:187], v[188:189], v[190:191]
	v_rcp_f32_e32 v188, v175
	v_add_f32_e32 v175, 1.0, v192
	v_rcp_f32_e32 v189, v175
	v_pk_fma_f32 v[182:183], v[132:133], v[182:183], v[144:145]
	s_nop 0
	v_pk_fma_f32 v[180:181], v[136:137], v[180:181], v[182:183]
	v_pk_fma_f32 v[182:183], v[184:185], v[188:189], v[184:185] neg_lo:[1,0,0] neg_hi:[1,0,0]
	v_pk_fma_f32 v[180:181], v[106:107], v[140:141], v[180:181]
	s_nop 0
	v_pk_mul_f32 v[180:181], v[180:181], v[182:183]
	v_cvt_pk_bf16_f32 v182, v186, v187
	v_cvt_pk_bf16_f32 v183, v180, v181
	v_mad_i64_i32 v[180:181], s[6:7], v205, s5, v[178:179]
	global_store_dwordx2 v[180:181], v[182:183], off offset:8
.LBB0_625:
	s_or_b64 exec, exec, s[0:1]
	v_mov_b32_dpp v194, v32 row_shr:2 row_mask:0xf bank_mask:0xf bound_ctrl:1
	v_mov_b32_dpp v192, v32 row_shr:1 row_mask:0xf bank_mask:0xf bound_ctrl:1
	v_mov_b32_dpp v190, v96 row_shr:2 row_mask:0xf bank_mask:0xf bound_ctrl:1
	v_mov_b32_dpp v188, v96 row_shr:1 row_mask:0xf bank_mask:0xf bound_ctrl:1
	v_mov_b32_dpp v195, v33 row_shr:2 row_mask:0xf bank_mask:0xf bound_ctrl:1
	v_mov_b32_dpp v193, v33 row_shr:1 row_mask:0xf bank_mask:0xf bound_ctrl:1
	v_mov_b32_dpp v191, v97 row_shr:2 row_mask:0xf bank_mask:0xf bound_ctrl:1
	v_mov_b32_dpp v189, v97 row_shr:1 row_mask:0xf bank_mask:0xf bound_ctrl:1
	v_mov_b32_dpp v186, v34 row_shr:2 row_mask:0xf bank_mask:0xf bound_ctrl:1
	v_mov_b32_dpp v184, v34 row_shr:1 row_mask:0xf bank_mask:0xf bound_ctrl:1
	v_mov_b32_dpp v182, v98 row_shr:2 row_mask:0xf bank_mask:0xf bound_ctrl:1
	v_mov_b32_dpp v180, v98 row_shr:1 row_mask:0xf bank_mask:0xf bound_ctrl:1
	v_mov_b32_dpp v187, v35 row_shr:2 row_mask:0xf bank_mask:0xf bound_ctrl:1
	v_mov_b32_dpp v185, v35 row_shr:1 row_mask:0xf bank_mask:0xf bound_ctrl:1
	v_mov_b32_dpp v183, v99 row_shr:2 row_mask:0xf bank_mask:0xf bound_ctrl:1
	v_mov_b32_dpp v181, v99 row_shr:1 row_mask:0xf bank_mask:0xf bound_ctrl:1
	s_and_saveexec_b64 s[0:1], s[40:41]
	s_cbranch_execz .LBB0_627
	s_nop 0
	v_pk_fma_f32 v[194:195], v[146:147], v[194:195], v[158:159]
	v_pk_fma_f32 v[186:187], v[148:149], v[186:187], v[160:161]
	v_pk_fma_f32 v[192:193], v[150:151], v[192:193], v[194:195]
	v_pk_fma_f32 v[184:185], v[152:153], v[184:185], v[186:187]
	v_pk_fma_f32 v[192:193], v[32:33], v[154:155], v[192:193]
	v_pk_fma_f32 v[184:185], v[34:35], v[156:157], v[184:185]
	v_mul_f32_e32 v175, 0x3dd2d3e8, v192
	v_fmaak_f32 v175, v192, v175, 0x40135761
	v_mul_f32_e32 v194, 0x3dd2d3e8, v193
	v_mul_f32_e32 v175, v192, v175
	v_fmaak_f32 v194, v193, v194, 0x40135761
	v_exp_f32_e32 v175, v175
	v_mul_f32_e32 v194, v193, v194
	v_exp_f32_e32 v195, v194
	v_mul_f32_e32 v186, 0x3dd2d3e8, v185
	v_add_f32_e32 v175, 1.0, v175
	v_rcp_f32_e32 v194, v175
	v_add_f32_e32 v175, 1.0, v195
	v_rcp_f32_e32 v195, v175
	v_mul_f32_e32 v175, 0x3dd2d3e8, v184
	v_fmaak_f32 v175, v184, v175, 0x40135761
	v_mul_f32_e32 v175, v184, v175
	v_fmaak_f32 v186, v185, v186, 0x40135761
	s_nop 0
	v_pk_fma_f32 v[190:191], v[130:131], v[190:191], v[142:143]
	v_exp_f32_e32 v175, v175
	v_mul_f32_e32 v186, v185, v186
	v_pk_fma_f32 v[188:189], v[134:135], v[188:189], v[190:191]
	v_pk_fma_f32 v[190:191], v[192:193], v[194:195], v[192:193] neg_lo:[1,0,0] neg_hi:[1,0,0]
	v_exp_f32_e32 v192, v186
	v_pk_fma_f32 v[188:189], v[96:97], v[138:139], v[188:189]
	v_add_f32_e32 v175, 1.0, v175
	v_pk_mul_f32 v[186:187], v[188:189], v[190:191]
	v_rcp_f32_e32 v188, v175
	v_add_f32_e32 v175, 1.0, v192
	v_rcp_f32_e32 v189, v175
	v_pk_fma_f32 v[182:183], v[132:133], v[182:183], v[144:145]
	s_nop 0
	v_pk_fma_f32 v[180:181], v[136:137], v[180:181], v[182:183]
	v_pk_fma_f32 v[182:183], v[184:185], v[188:189], v[184:185] neg_lo:[1,0,0] neg_hi:[1,0,0]
	v_pk_fma_f32 v[180:181], v[98:99], v[140:141], v[180:181]
	s_nop 0
	v_pk_mul_f32 v[180:181], v[180:181], v[182:183]
	v_cvt_pk_bf16_f32 v182, v186, v187
	v_cvt_pk_bf16_f32 v183, v180, v181
	v_mad_i64_i32 v[180:181], s[6:7], v206, s5, v[178:179]
	global_store_dwordx2 v[180:181], v[182:183], off offset:8
.LBB0_627:
	s_or_b64 exec, exec, s[0:1]
	v_mov_b32_dpp v194, v24 row_shr:2 row_mask:0xf bank_mask:0xf bound_ctrl:1
	v_mov_b32_dpp v192, v24 row_shr:1 row_mask:0xf bank_mask:0xf bound_ctrl:1
	v_mov_b32_dpp v190, v88 row_shr:2 row_mask:0xf bank_mask:0xf bound_ctrl:1
	v_mov_b32_dpp v188, v88 row_shr:1 row_mask:0xf bank_mask:0xf bound_ctrl:1
	v_mov_b32_dpp v195, v25 row_shr:2 row_mask:0xf bank_mask:0xf bound_ctrl:1
	v_mov_b32_dpp v193, v25 row_shr:1 row_mask:0xf bank_mask:0xf bound_ctrl:1
	v_mov_b32_dpp v191, v89 row_shr:2 row_mask:0xf bank_mask:0xf bound_ctrl:1
	v_mov_b32_dpp v189, v89 row_shr:1 row_mask:0xf bank_mask:0xf bound_ctrl:1
	v_mov_b32_dpp v186, v26 row_shr:2 row_mask:0xf bank_mask:0xf bound_ctrl:1
	v_mov_b32_dpp v184, v26 row_shr:1 row_mask:0xf bank_mask:0xf bound_ctrl:1
	v_mov_b32_dpp v182, v90 row_shr:2 row_mask:0xf bank_mask:0xf bound_ctrl:1
	v_mov_b32_dpp v180, v90 row_shr:1 row_mask:0xf bank_mask:0xf bound_ctrl:1
	v_mov_b32_dpp v187, v27 row_shr:2 row_mask:0xf bank_mask:0xf bound_ctrl:1
	v_mov_b32_dpp v185, v27 row_shr:1 row_mask:0xf bank_mask:0xf bound_ctrl:1
	v_mov_b32_dpp v183, v91 row_shr:2 row_mask:0xf bank_mask:0xf bound_ctrl:1
	v_mov_b32_dpp v181, v91 row_shr:1 row_mask:0xf bank_mask:0xf bound_ctrl:1
	s_and_saveexec_b64 s[0:1], s[40:41]
	s_cbranch_execz .LBB0_629
	s_nop 0
	v_pk_fma_f32 v[194:195], v[146:147], v[194:195], v[158:159]
	v_pk_fma_f32 v[186:187], v[148:149], v[186:187], v[160:161]
	v_pk_fma_f32 v[192:193], v[150:151], v[192:193], v[194:195]
	v_pk_fma_f32 v[184:185], v[152:153], v[184:185], v[186:187]
	v_pk_fma_f32 v[192:193], v[24:25], v[154:155], v[192:193]
	v_pk_fma_f32 v[184:185], v[26:27], v[156:157], v[184:185]
	v_mul_f32_e32 v175, 0x3dd2d3e8, v192
	v_fmaak_f32 v175, v192, v175, 0x40135761
	v_mul_f32_e32 v194, 0x3dd2d3e8, v193
	v_mul_f32_e32 v175, v192, v175
	v_fmaak_f32 v194, v193, v194, 0x40135761
	v_exp_f32_e32 v175, v175
	v_mul_f32_e32 v194, v193, v194
	v_exp_f32_e32 v195, v194
	v_mul_f32_e32 v186, 0x3dd2d3e8, v185
	v_add_f32_e32 v175, 1.0, v175
	v_rcp_f32_e32 v194, v175
	v_add_f32_e32 v175, 1.0, v195
	v_rcp_f32_e32 v195, v175
	v_mul_f32_e32 v175, 0x3dd2d3e8, v184
	v_fmaak_f32 v175, v184, v175, 0x40135761
	v_mul_f32_e32 v175, v184, v175
	v_fmaak_f32 v186, v185, v186, 0x40135761
	s_nop 0
	v_pk_fma_f32 v[190:191], v[130:131], v[190:191], v[142:143]
	v_exp_f32_e32 v175, v175
	v_mul_f32_e32 v186, v185, v186
	v_pk_fma_f32 v[188:189], v[134:135], v[188:189], v[190:191]
	v_pk_fma_f32 v[190:191], v[192:193], v[194:195], v[192:193] neg_lo:[1,0,0] neg_hi:[1,0,0]
	v_exp_f32_e32 v192, v186
	v_pk_fma_f32 v[188:189], v[88:89], v[138:139], v[188:189]
	v_add_f32_e32 v175, 1.0, v175
	v_pk_mul_f32 v[186:187], v[188:189], v[190:191]
	v_rcp_f32_e32 v188, v175
	v_add_f32_e32 v175, 1.0, v192
	v_rcp_f32_e32 v189, v175
	v_pk_fma_f32 v[182:183], v[132:133], v[182:183], v[144:145]
	s_nop 0
	v_pk_fma_f32 v[180:181], v[136:137], v[180:181], v[182:183]
	v_pk_fma_f32 v[182:183], v[184:185], v[188:189], v[184:185] neg_lo:[1,0,0] neg_hi:[1,0,0]
	v_pk_fma_f32 v[180:181], v[90:91], v[140:141], v[180:181]
	s_nop 0
	v_pk_mul_f32 v[180:181], v[180:181], v[182:183]
	v_cvt_pk_bf16_f32 v182, v186, v187
	v_cvt_pk_bf16_f32 v183, v180, v181
	v_mad_i64_i32 v[180:181], s[6:7], v173, s5, v[178:179]
	global_store_dwordx2 v[180:181], v[182:183], off offset:8
.LBB0_629:
	s_or_b64 exec, exec, s[0:1]
	v_mov_b32_dpp v194, v16 row_shr:2 row_mask:0xf bank_mask:0xf bound_ctrl:1
	v_mov_b32_dpp v192, v16 row_shr:1 row_mask:0xf bank_mask:0xf bound_ctrl:1
	v_mov_b32_dpp v190, v80 row_shr:2 row_mask:0xf bank_mask:0xf bound_ctrl:1
	v_mov_b32_dpp v188, v80 row_shr:1 row_mask:0xf bank_mask:0xf bound_ctrl:1
	v_mov_b32_dpp v195, v17 row_shr:2 row_mask:0xf bank_mask:0xf bound_ctrl:1
	v_mov_b32_dpp v193, v17 row_shr:1 row_mask:0xf bank_mask:0xf bound_ctrl:1
	v_mov_b32_dpp v191, v81 row_shr:2 row_mask:0xf bank_mask:0xf bound_ctrl:1
	v_mov_b32_dpp v189, v81 row_shr:1 row_mask:0xf bank_mask:0xf bound_ctrl:1
	v_mov_b32_dpp v186, v18 row_shr:2 row_mask:0xf bank_mask:0xf bound_ctrl:1
	v_mov_b32_dpp v184, v18 row_shr:1 row_mask:0xf bank_mask:0xf bound_ctrl:1
	v_mov_b32_dpp v182, v82 row_shr:2 row_mask:0xf bank_mask:0xf bound_ctrl:1
	v_mov_b32_dpp v180, v82 row_shr:1 row_mask:0xf bank_mask:0xf bound_ctrl:1
	v_mov_b32_dpp v187, v19 row_shr:2 row_mask:0xf bank_mask:0xf bound_ctrl:1
	v_mov_b32_dpp v185, v19 row_shr:1 row_mask:0xf bank_mask:0xf bound_ctrl:1
	v_mov_b32_dpp v183, v83 row_shr:2 row_mask:0xf bank_mask:0xf bound_ctrl:1
	v_mov_b32_dpp v181, v83 row_shr:1 row_mask:0xf bank_mask:0xf bound_ctrl:1
	s_and_saveexec_b64 s[0:1], s[40:41]
	s_cbranch_execz .LBB0_631
	s_nop 0
	v_pk_fma_f32 v[194:195], v[146:147], v[194:195], v[158:159]
	v_pk_fma_f32 v[186:187], v[148:149], v[186:187], v[160:161]
	v_pk_fma_f32 v[192:193], v[150:151], v[192:193], v[194:195]
	v_pk_fma_f32 v[184:185], v[152:153], v[184:185], v[186:187]
	v_pk_fma_f32 v[192:193], v[16:17], v[154:155], v[192:193]
	v_pk_fma_f32 v[184:185], v[18:19], v[156:157], v[184:185]
	v_mul_f32_e32 v173, 0x3dd2d3e8, v192
	v_fmaak_f32 v173, v192, v173, 0x40135761
	v_mul_f32_e32 v175, 0x3dd2d3e8, v193
	v_mul_f32_e32 v173, v192, v173
	v_fmaak_f32 v175, v193, v175, 0x40135761
	v_exp_f32_e32 v173, v173
	v_mul_f32_e32 v175, v193, v175
	v_exp_f32_e32 v175, v175
	s_nop 0
	v_pk_fma_f32 v[190:191], v[130:131], v[190:191], v[142:143]
	v_add_f32_e32 v173, 1.0, v173
	v_rcp_f32_e32 v194, v173
	v_add_f32_e32 v173, 1.0, v175
	v_rcp_f32_e32 v195, v173
	v_mul_f32_e32 v173, 0x3dd2d3e8, v184
	v_fmaak_f32 v173, v184, v173, 0x40135761
	v_mul_f32_e32 v175, 0x3dd2d3e8, v185
	v_mul_f32_e32 v173, v184, v173
	v_fmaak_f32 v175, v185, v175, 0x40135761
	v_exp_f32_e32 v173, v173
	v_mul_f32_e32 v175, v185, v175
	v_exp_f32_e32 v175, v175
	v_pk_fma_f32 v[188:189], v[134:135], v[188:189], v[190:191]
	v_pk_fma_f32 v[190:191], v[192:193], v[194:195], v[192:193] neg_lo:[1,0,0] neg_hi:[1,0,0]
	v_pk_fma_f32 v[188:189], v[80:81], v[138:139], v[188:189]
	v_add_f32_e32 v173, 1.0, v173
	v_pk_mul_f32 v[186:187], v[188:189], v[190:191]
	v_rcp_f32_e32 v188, v173
	v_add_f32_e32 v173, 1.0, v175
	v_rcp_f32_e32 v189, v173
	v_pk_fma_f32 v[182:183], v[132:133], v[182:183], v[144:145]
	s_nop 0
	v_pk_fma_f32 v[180:181], v[136:137], v[180:181], v[182:183]
	v_pk_fma_f32 v[182:183], v[184:185], v[188:189], v[184:185] neg_lo:[1,0,0] neg_hi:[1,0,0]
	v_pk_fma_f32 v[180:181], v[82:83], v[140:141], v[180:181]
	s_nop 0
	v_pk_mul_f32 v[180:181], v[180:181], v[182:183]
	v_cvt_pk_bf16_f32 v182, v186, v187
	v_cvt_pk_bf16_f32 v183, v180, v181
	v_mad_i64_i32 v[180:181], s[6:7], v207, s5, v[178:179]
	global_store_dwordx2 v[180:181], v[182:183], off offset:8
.LBB0_631:
	s_or_b64 exec, exec, s[0:1]
	v_mov_b32_dpp v194, v8 row_shr:2 row_mask:0xf bank_mask:0xf bound_ctrl:1
	v_mov_b32_dpp v192, v8 row_shr:1 row_mask:0xf bank_mask:0xf bound_ctrl:1
	v_mov_b32_dpp v190, v72 row_shr:2 row_mask:0xf bank_mask:0xf bound_ctrl:1
	v_mov_b32_dpp v188, v72 row_shr:1 row_mask:0xf bank_mask:0xf bound_ctrl:1
	v_mov_b32_dpp v195, v9 row_shr:2 row_mask:0xf bank_mask:0xf bound_ctrl:1
	v_mov_b32_dpp v193, v9 row_shr:1 row_mask:0xf bank_mask:0xf bound_ctrl:1
	v_mov_b32_dpp v191, v73 row_shr:2 row_mask:0xf bank_mask:0xf bound_ctrl:1
	v_mov_b32_dpp v189, v73 row_shr:1 row_mask:0xf bank_mask:0xf bound_ctrl:1
	v_mov_b32_dpp v186, v10 row_shr:2 row_mask:0xf bank_mask:0xf bound_ctrl:1
	v_mov_b32_dpp v184, v10 row_shr:1 row_mask:0xf bank_mask:0xf bound_ctrl:1
	v_mov_b32_dpp v182, v74 row_shr:2 row_mask:0xf bank_mask:0xf bound_ctrl:1
	v_mov_b32_dpp v180, v74 row_shr:1 row_mask:0xf bank_mask:0xf bound_ctrl:1
	v_mov_b32_dpp v187, v11 row_shr:2 row_mask:0xf bank_mask:0xf bound_ctrl:1
	v_mov_b32_dpp v185, v11 row_shr:1 row_mask:0xf bank_mask:0xf bound_ctrl:1
	v_mov_b32_dpp v183, v75 row_shr:2 row_mask:0xf bank_mask:0xf bound_ctrl:1
	v_mov_b32_dpp v181, v75 row_shr:1 row_mask:0xf bank_mask:0xf bound_ctrl:1
	s_and_saveexec_b64 s[0:1], s[40:41]
	s_cbranch_execz .LBB0_633
	s_nop 0
	v_pk_fma_f32 v[194:195], v[146:147], v[194:195], v[158:159]
	v_pk_fma_f32 v[186:187], v[148:149], v[186:187], v[160:161]
	v_pk_fma_f32 v[192:193], v[150:151], v[192:193], v[194:195]
	v_pk_fma_f32 v[184:185], v[152:153], v[184:185], v[186:187]
	v_pk_fma_f32 v[192:193], v[8:9], v[154:155], v[192:193]
	v_pk_fma_f32 v[184:185], v[10:11], v[156:157], v[184:185]
	v_mul_f32_e32 v173, 0x3dd2d3e8, v192
	v_fmaak_f32 v173, v192, v173, 0x40135761
	v_mul_f32_e32 v175, 0x3dd2d3e8, v193
	v_mul_f32_e32 v173, v192, v173
	v_fmaak_f32 v175, v193, v175, 0x40135761
	v_exp_f32_e32 v173, v173
	v_mul_f32_e32 v175, v193, v175
	v_exp_f32_e32 v175, v175
	s_nop 0
	v_pk_fma_f32 v[190:191], v[130:131], v[190:191], v[142:143]
	v_add_f32_e32 v173, 1.0, v173
	v_rcp_f32_e32 v194, v173
	v_add_f32_e32 v173, 1.0, v175
	v_rcp_f32_e32 v195, v173
	v_mul_f32_e32 v173, 0x3dd2d3e8, v184
	v_fmaak_f32 v173, v184, v173, 0x40135761
	v_mul_f32_e32 v175, 0x3dd2d3e8, v185
	v_mul_f32_e32 v173, v184, v173
	v_fmaak_f32 v175, v185, v175, 0x40135761
	v_exp_f32_e32 v173, v173
	v_mul_f32_e32 v175, v185, v175
	v_exp_f32_e32 v175, v175
	v_pk_fma_f32 v[188:189], v[134:135], v[188:189], v[190:191]
	v_pk_fma_f32 v[190:191], v[192:193], v[194:195], v[192:193] neg_lo:[1,0,0] neg_hi:[1,0,0]
	v_pk_fma_f32 v[188:189], v[72:73], v[138:139], v[188:189]
	v_add_f32_e32 v173, 1.0, v173
	v_pk_mul_f32 v[186:187], v[188:189], v[190:191]
	v_rcp_f32_e32 v188, v173
	v_add_f32_e32 v173, 1.0, v175
	v_rcp_f32_e32 v189, v173
	v_pk_fma_f32 v[182:183], v[132:133], v[182:183], v[144:145]
	s_nop 0
	v_pk_fma_f32 v[180:181], v[136:137], v[180:181], v[182:183]
	v_pk_fma_f32 v[182:183], v[184:185], v[188:189], v[184:185] neg_lo:[1,0,0] neg_hi:[1,0,0]
	v_pk_fma_f32 v[180:181], v[74:75], v[140:141], v[180:181]
	s_nop 0
	v_pk_mul_f32 v[180:181], v[180:181], v[182:183]
	v_cvt_pk_bf16_f32 v182, v186, v187
	v_cvt_pk_bf16_f32 v183, v180, v181
	v_mad_i64_i32 v[180:181], s[6:7], v208, s5, v[178:179]
	global_store_dwordx2 v[180:181], v[182:183], off offset:8
.LBB0_633:
	s_or_b64 exec, exec, s[0:1]
	v_mov_b32_dpp v194, v0 row_shr:2 row_mask:0xf bank_mask:0xf bound_ctrl:1
	v_mov_b32_dpp v192, v0 row_shr:1 row_mask:0xf bank_mask:0xf bound_ctrl:1
	v_mov_b32_dpp v190, v60 row_shr:2 row_mask:0xf bank_mask:0xf bound_ctrl:1
	v_mov_b32_dpp v188, v60 row_shr:1 row_mask:0xf bank_mask:0xf bound_ctrl:1
	v_mov_b32_dpp v195, v1 row_shr:2 row_mask:0xf bank_mask:0xf bound_ctrl:1
	v_mov_b32_dpp v193, v1 row_shr:1 row_mask:0xf bank_mask:0xf bound_ctrl:1
	v_mov_b32_dpp v191, v61 row_shr:2 row_mask:0xf bank_mask:0xf bound_ctrl:1
	v_mov_b32_dpp v189, v61 row_shr:1 row_mask:0xf bank_mask:0xf bound_ctrl:1
	v_mov_b32_dpp v186, v2 row_shr:2 row_mask:0xf bank_mask:0xf bound_ctrl:1
	v_mov_b32_dpp v184, v2 row_shr:1 row_mask:0xf bank_mask:0xf bound_ctrl:1
	v_mov_b32_dpp v182, v62 row_shr:2 row_mask:0xf bank_mask:0xf bound_ctrl:1
	v_mov_b32_dpp v180, v62 row_shr:1 row_mask:0xf bank_mask:0xf bound_ctrl:1
	v_mov_b32_dpp v187, v3 row_shr:2 row_mask:0xf bank_mask:0xf bound_ctrl:1
	v_mov_b32_dpp v185, v3 row_shr:1 row_mask:0xf bank_mask:0xf bound_ctrl:1
	v_mov_b32_dpp v183, v63 row_shr:2 row_mask:0xf bank_mask:0xf bound_ctrl:1
	v_mov_b32_dpp v181, v63 row_shr:1 row_mask:0xf bank_mask:0xf bound_ctrl:1
	s_and_saveexec_b64 s[0:1], s[40:41]
	s_cbranch_execz .LBB0_635
	s_nop 0
	v_pk_fma_f32 v[146:147], v[146:147], v[194:195], v[158:159]
	s_nop 0
	v_pk_fma_f32 v[130:131], v[130:131], v[190:191], v[142:143]
	v_pk_fma_f32 v[146:147], v[150:151], v[192:193], v[146:147]
	v_pk_fma_f32 v[130:131], v[134:135], v[188:189], v[130:131]
	v_pk_fma_f32 v[146:147], v[0:1], v[154:155], v[146:147]
	v_pk_fma_f32 v[130:131], v[60:61], v[138:139], v[130:131]
	v_mul_f32_e32 v150, 0x3dd2d3e8, v146
	v_mul_f32_e32 v151, 0x3dd2d3e8, v147
	v_fmaak_f32 v150, v146, v150, 0x40135761
	v_fmaak_f32 v151, v147, v151, 0x40135761
	v_mul_f32_e32 v150, v146, v150
	v_mul_f32_e32 v151, v147, v151
	v_exp_f32_e32 v150, v150
	v_exp_f32_e32 v151, v151
	v_pk_fma_f32 v[138:139], v[148:149], v[186:187], v[160:161]
	v_pk_fma_f32 v[132:133], v[132:133], v[182:183], v[144:145]
	v_pk_fma_f32 v[138:139], v[152:153], v[184:185], v[138:139]
	v_add_f32_e32 v150, 1.0, v150
	v_pk_fma_f32 v[138:139], v[2:3], v[156:157], v[138:139]
	v_add_f32_e32 v151, 1.0, v151
	v_mul_f32_e32 v142, 0x3dd2d3e8, v138
	v_mul_f32_e32 v143, 0x3dd2d3e8, v139
	v_fmaak_f32 v142, v138, v142, 0x40135761
	v_fmaak_f32 v143, v139, v143, 0x40135761
	v_rcp_f32_e32 v150, v150
	v_rcp_f32_e32 v151, v151
	v_mul_f32_e32 v142, v138, v142
	v_mul_f32_e32 v143, v139, v143
	v_exp_f32_e32 v142, v142
	v_exp_f32_e32 v143, v143
	v_pk_fma_f32 v[134:135], v[146:147], v[150:151], v[146:147] neg_lo:[1,0,0] neg_hi:[1,0,0]
	v_pk_fma_f32 v[132:133], v[136:137], v[180:181], v[132:133]
	v_pk_mul_f32 v[130:131], v[130:131], v[134:135]
	v_add_f32_e32 v134, 1.0, v142
	v_add_f32_e32 v135, 1.0, v143
	v_rcp_f32_e32 v134, v134
	v_rcp_f32_e32 v135, v135
	v_pk_fma_f32 v[132:133], v[62:63], v[140:141], v[132:133]
	v_cvt_pk_bf16_f32 v130, v130, v131
	v_pk_fma_f32 v[134:135], v[138:139], v[134:135], v[138:139] neg_lo:[1,0,0] neg_hi:[1,0,0]
	s_nop 0
	v_pk_mul_f32 v[132:133], v[132:133], v[134:135]
	s_nop 0
	v_cvt_pk_bf16_f32 v131, v132, v133
	v_mad_i64_i32 v[132:133], s[6:7], v209, s5, v[178:179]
	global_store_dwordx2 v[132:133], v[130:131], off offset:8
